# second load-segment wait of each tile also counts the epilogue's guaranteed VMEM ops; GEMM prologue waits for all of K-tile 1 so the first tile stays safe
# baseline (speedup 1.0000x reference)
; #define PG8_STAGE(bufoff, gbase, voff) do { _Pragma("unroll") for (int _i = 0; _i < 2; ++_i) \
;         __builtin_amdgcn_global_load_lds((const unsigned*)((const char*)(gbase) + (voff)[_i]), (LAS unsigned*)(lds + (bufoff) + ldsw + _i * 8192), 16, 0, 0); } while (0)
; #define PG8_WAIT_V(n) asm volatile("s_waitcnt vmcnt(" #n ")" ::: "memory")
; #define PG8_BAR __builtin_amdgcn_s_barrier()
; template <class Epi, class AMap>
; __device__ __forceinline__ void gemm_phase(LAS unsigned char* lds, const AMap am, const int lda, const h16* Bt, const int ldb, const int M, const int N, const int K, const Epi& E) {
;     ...
;     for (int i = 0; i < 2; ++i) { int R, C; stage_rc(tid * 16 + i * 8192, R, C); const int Rb = Epi::PERM ? ((R & ~31) + perm32(R & 31)) : R;
;         voffA[i] = (unsigned)(R * lda + C) * 2u; voffB[i] = (unsigned)(Rb * ldb + C) * 2u; }
;     const size_t kstep = (size_t)(BK * 2);
;     const size_t hstepA = (size_t)HALF * lda * 2, hstepB = (size_t)HALF * ldb * 2;
;     const size_t tstepA = 2 * hstepA, tstepB = 2 * hstepB;
;     const unsigned ldsw = (unsigned)wid * 1024u;
;     const int aoff = lds_byte(wr * 64 + fr, fq * 8), boff = lds_byte(wc * 32 + fr, fq * 8);
;     ...
;     PG8_STAGE(PG8_SB(0, 0), cB, voffB); PG8_STAGE(PG8_SA(0, 0), cA, voffA); PG8_STAGE(PG8_SB(0, 1), cB + hstepB, voffB); PG8_STAGE(PG8_SA(0, 1), cA + hstepA, voffA);
;     if (wr == 1) PG8_BAR;
;     PG8_WAIT_V(4); PG8_BAR;
;     PG8_STAGE(PG8_SB(1, 0), cB + kstep, voffB); PG8_STAGE(PG8_SA(1, 0), cA + kstep, voffA); PG8_STAGE(PG8_SB(1, 1), cB + hstepB + kstep, voffB);
;     PG8_WAIT_V(6); PG8_BAR;
.LBB0_49:
	v_lshrrev_b32_e32 v20, 1, v10
	s_lshr_b32 s20, s20, 2
	v_and_b32_e32 v20, 24, v20
	s_lshl_b32 s0, s0, 5
	s_sext_i32_i8 s50, s20
	v_and_b32_e32 v11, 15, v10
	v_lshlrev_b32_e32 v21, 1, v20
	v_lshlrev_b32_e32 v10, 2, v10
	s_and_b32 s20, s0, 0x60
	v_lshl_add_u64 v[12:13], s[26:27], 0, v[0:1]
	v_mov_b32_e32 v135, v1
	v_lshl_or_b32 v146, s1, 6, v11
	v_lshl_or_b32 v11, v11, 6, v21
	s_lshl_b32 s1, s1, 13
	v_and_b32_e32 v10, 32, v10
	s_lshl_b32 s0, s20, 7
	v_lshl_add_u64 v[14:15], s[26:27], 0, v[134:135]
	v_mov_b32_e32 v131, v1
	v_bitop3_b32 v21, v11, s1, v10 bitop3:0xde
	v_bitop3_b32 v147, v11, s0, v10 bitop3:0xde
	s_add_i32 m0, s63, 0x18000
	v_lshl_add_u64 v[10:11], v[12:13], 0, s[92:93]
	v_lshl_add_u64 v[16:17], s[22:23], 0, v[130:131]
	v_mov_b32_e32 v133, v1
	s_waitcnt vmcnt(0)
	s_barrier
	global_load_lds_dwordx4 v[10:11], off
	v_lshl_add_u64 v[10:11], v[14:15], 0, s[92:93]
	s_add_i32 m0, s63, 0x1a000
	s_add_i32 s69, s63, 0x8000
	s_add_i32 s70, s63, 0xa000
	v_lshl_add_u64 v[18:19], s[22:23], 0, v[132:133]
	global_load_lds_dwordx4 v[10:11], off
	v_lshl_add_u64 v[10:11], v[16:17], 0, s[92:93]
	s_mov_b32 m0, s69
	s_add_u32 s0, s26, 0x158080
	global_load_lds_dwordx4 v[10:11], off
	v_lshl_add_u64 v[10:11], v[18:19], 0, s[92:93]
	s_mov_b32 m0, s70
	s_addc_u32 s1, s27, 0
	global_load_lds_dwordx4 v[10:11], off
	s_add_i32 m0, s63, 0x1c000
	v_lshl_add_u64 v[10:11], s[0:1], 0, v[0:1]
	global_load_lds_dwordx4 v[10:11], off
	v_lshl_add_u64 v[10:11], s[0:1], 0, v[134:135]
	s_add_i32 m0, s63, 0x1e000
	s_mov_b32 s4, 0x15800
	global_load_lds_dwordx4 v[10:11], off
	v_lshrrev_b32_e32 v10, 1, v2
	v_mul_lo_u32 v2, v4, s3
	v_mad_u64_u32 v[10:11], s[0:1], v10, s4, v[2:3]
	v_or_b32_e32 v2, v10, v3
	v_add_lshl_u32 v2, v2, v5, 1
	v_mov_b32_e32 v3, v1
	s_mov_b64 s[6:7], 0x158080
	v_lshl_add_u64 v[136:137], v[2:3], 0, s[6:7]
	v_lshrrev_b32_e32 v3, 1, v6
	v_mul_lo_u32 v2, v8, s3
	v_mad_u64_u32 v[2:3], s[0:1], v3, s4, v[2:3]
	s_waitcnt vmcnt(0)
	v_or_b32_e32 v2, v2, v7
	v_add_lshl_u32 v2, v2, v9, 1
	v_mov_b32_e32 v3, v1
	v_or_b32_e32 v148, s20, v20
	v_lshl_add_u64 v[138:139], v[2:3], 0, s[6:7]
	s_mov_b32 s71, 0
	v_add_u32_e32 v149, 0, v21
	s_mov_b64 s[6:7], s[40:41]
	s_barrier

; #define PG8_STAGE(bufoff, gbase, voff) do { _Pragma("unroll") for (int _i = 0; _i < 2; ++_i) \
;         __builtin_amdgcn_global_load_lds((const unsigned*)((const char*)(gbase) + (voff)[_i]), (LAS unsigned*)(lds + (bufoff) + ldsw + _i * 8192), 16, 0, 0); } while (0)
; #define PG8_LDA(dst, b, h) do { _Pragma("unroll") for (int m = 0; m < 4; ++m) _Pragma("unroll") for (int k = 0; k < 2; ++k) dst[m][k] = *(const LAS h16x8*)(lds + PG8_SA(b, h) + aoff + m * 2048 + k * 1024); } while (0)
; #define PG8_LDB(dst, b, h) do { _Pragma("unroll") for (int n = 0; n < 2; ++n) _Pragma("unroll") for (int k = 0; k < 2; ++k) dst[n][k] = *(const LAS h16x8*)(lds + PG8_SB(b, h) + boff + n * 2048 + k * 1024); } while (0)
; #define PG8_MMA(ai, bj, At, Bt_) do { __builtin_amdgcn_s_setprio(1); _Pragma("unroll") for (int m = 0; m < 4; ++m) _Pragma("unroll") for (int n = 0; n < 2; ++n) _Pragma("unroll") for (int k = 0; k < 2; ++k) \
;         acc[ai][bj][m][n] = __builtin_amdgcn_mfma_f32_16x16x32_f16(Bt_[n][k], At[m][k], acc[ai][bj][m][n], 0, 0, 0); __builtin_amdgcn_s_setprio(0); } while (0)
; #define PG8_WAIT_L(n) asm volatile("s_waitcnt lgkmcnt(" #n ")" ::: "memory")
; #define PG8_BAR __builtin_amdgcn_s_barrier()
; #define PG8_SCHED __builtin_amdgcn_sched_barrier(0)
; template <class Epi, class AMap>
; __device__ __forceinline__ void gemm_phase(LAS unsigned char* lds, const AMap am, const int lda, const h16* Bt, const int ldb, const int M, const int N, const int K, const Epi& E) {
;     ...
;             const bool last = (t == nt - 2);
;             const char* a1 = cA + (size_t)(t + 1) * kstep;
;             const char* a2 = last ? nA : cA + (size_t)(t + 2) * kstep; const char* b2 = last ? nB : cB + (size_t)(t + 2) * kstep;
;             const char* a3 = a2 + kstep; const char* b3 = b2 + kstep;
;             PG8_LDB(B0, 0, 0); PG8_SCHED; PG8_LDA(At, 0, 0); PG8_STAGE(PG8_SA(1, 1), a1 + hstepA, voffA);
;             PG8_WAIT_L(8); PG8_BAR; PG8_WAIT_L(0); PG8_MMA(0, 0, At, B0); PG8_BAR; PG8_SCHED;
;             PG8_LDB(B1, 0, 1); PG8_STAGE(PG8_SB(0, 0), b2, voffB);
;             PG8_BAR; PG8_WAIT_L(0); PG8_MMA(0, 1, At, B1); PG8_BAR;
;             PG8_LDA(At, 0, 1); PG8_STAGE(PG8_SA(0, 0), a2, voffA);
;             PG8_BAR; PG8_WAIT_L(0); PG8_MMA(1, 0, At, B0); PG8_BAR; PG8_SCHED;
;             PG8_STAGE(PG8_SB(0, 1), b2 + hstepB, voffB);
.Lg4p_61:
	s_add_u32 s26, s22, 0x100
	s_addc_u32 s27, s23, 0
	s_add_i32 s51, 0, 0x10000
	v_add_u32_e32 v144, s51, v147
	ds_read_b128 v[140:143], v144
	ds_read_b128 v[150:153], v144 offset:1024
	ds_read_b128 v[154:157], v144 offset:2048
	ds_read_b128 v[158:161], v144 offset:3072
	s_cmpk_eq_i32 s29, 0x52
	s_cselect_b32 s45, s1, s27
	s_cselect_b32 s44, s0, s26
	s_cselect_b32 s43, s41, s21
	s_cselect_b32 s42, s40, s20
	v_lshl_add_u64 v[144:145], s[22:23], 0, v[136:137]
	s_add_i32 m0, s63, 0xc000
	ds_read_b128 v[162:165], v149
	ds_read_b128 v[166:169], v149 offset:1024
	ds_read_b128 v[170:173], v149 offset:2048
	ds_read_b128 v[174:177], v149 offset:3072
	ds_read_b128 v[178:181], v149 offset:4096
	ds_read_b128 v[182:185], v149 offset:5120
	ds_read_b128 v[186:189], v149 offset:6144
	ds_read_b128 v[190:193], v149 offset:7168
	global_load_lds_dwordx4 v[144:145], off
	v_lshl_add_u64 v[144:145], s[22:23], 0, v[138:139]
	s_add_i32 m0, s63, 0xe000
	s_nop 0
	global_load_lds_dwordx4 v[144:145], off
	s_waitcnt lgkmcnt(11)
	s_add_i32 s60, 0, 0x14000
	v_add_u32_e32 v144, s60, v147
	s_add_i32 s22, s51, s48
	ds_read_b128 v[194:197], v144
	ds_read_b128 v[198:201], v144 offset:1024
	ds_read_b128 v[202:205], v144 offset:2048
	ds_read_b128 v[220:223], v144 offset:3072
	s_waitcnt vmcnt(40) lgkmcnt(0)
	s_barrier
	v_mfma_f32_16x16x32_f16 v[126:129], v[140:143], v[162:165], 0
	v_mfma_f32_16x16x32_f16 v[122:125], v[154:157], v[162:165], 0
	v_mfma_f32_16x16x32_f16 v[110:113], v[140:143], v[170:173], 0
	v_mfma_f32_16x16x32_f16 v[106:109], v[154:157], v[170:173], 0
	v_mfma_f32_16x16x32_f16 v[94:97], v[140:143], v[178:181], 0
	v_mfma_f32_16x16x32_f16 v[90:93], v[154:157], v[178:181], 0
	v_mfma_f32_16x16x32_f16 v[78:81], v[140:143], v[186:189], 0
	v_mfma_f32_16x16x32_f16 v[74:77], v[154:157], v[186:189], 0
	v_mfma_f32_16x16x32_f16 v[126:129], v[150:153], v[166:169], v[126:129]
	v_mfma_f32_16x16x32_f16 v[122:125], v[158:161], v[166:169], v[122:125]
	v_mfma_f32_16x16x32_f16 v[110:113], v[150:153], v[174:177], v[110:113]
	v_mfma_f32_16x16x32_f16 v[106:109], v[158:161], v[174:177], v[106:109]
	v_mfma_f32_16x16x32_f16 v[94:97], v[150:153], v[182:185], v[94:97]
	v_mfma_f32_16x16x32_f16 v[90:93], v[158:161], v[182:185], v[90:93]
	v_mfma_f32_16x16x32_f16 v[78:81], v[150:153], v[190:193], v[78:81]
	v_mfma_f32_16x16x32_f16 v[74:77], v[158:161], v[190:193], v[74:77]
	v_mfma_f32_16x16x32_f16 v[118:121], v[194:197], v[162:165], 0
	v_mfma_f32_16x16x32_f16 v[114:117], v[202:205], v[162:165], 0
	v_mfma_f32_16x16x32_f16 v[102:105], v[194:197], v[170:173], 0
	v_mfma_f32_16x16x32_f16 v[98:101], v[202:205], v[170:173], 0
	v_mfma_f32_16x16x32_f16 v[86:89], v[194:197], v[178:181], 0
	v_mfma_f32_16x16x32_f16 v[82:85], v[202:205], v[178:181], 0
	v_mfma_f32_16x16x32_f16 v[70:73], v[194:197], v[186:189], 0
	v_mfma_f32_16x16x32_f16 v[66:69], v[202:205], v[186:189], 0
	v_mfma_f32_16x16x32_f16 v[118:121], v[198:201], v[166:169], v[118:121]
	v_mfma_f32_16x16x32_f16 v[114:117], v[220:223], v[166:169], v[114:117]
	v_mfma_f32_16x16x32_f16 v[102:105], v[198:201], v[174:177], v[102:105]
	v_mfma_f32_16x16x32_f16 v[98:101], v[220:223], v[174:177], v[98:101]
	v_mfma_f32_16x16x32_f16 v[86:89], v[198:201], v[182:185], v[86:89]
	v_mfma_f32_16x16x32_f16 v[82:85], v[220:223], v[182:185], v[82:85]
	v_mfma_f32_16x16x32_f16 v[70:73], v[198:201], v[190:193], v[70:73]
	v_mfma_f32_16x16x32_f16 v[66:69], v[220:223], v[190:193], v[66:69]
	s_barrier
	v_lshl_add_u64 v[144:145], s[42:43], 0, v[0:1]
	s_mov_b32 m0, s22
	v_lshl_add_u64 v[206:207], s[42:43], 0, v[134:135]
	global_load_lds_dwordx4 v[144:145], off
	s_add_i32 m0, s22, 0x2000
	s_nop 0
	global_load_lds_dwordx4 v[206:207], off
	s_mov_b32 m0, s63
	v_lshl_add_u64 v[212:213], s[44:45], 0, v[130:131]
	ds_read_b128 v[162:165], v149 offset:16384
	ds_read_b128 v[166:169], v149 offset:17408
	ds_read_b128 v[170:173], v149 offset:18432
	ds_read_b128 v[174:177], v149 offset:19456
	ds_read_b128 v[178:181], v149 offset:20480
	ds_read_b128 v[182:185], v149 offset:21504
	ds_read_b128 v[186:189], v149 offset:22528
	ds_read_b128 v[190:193], v149 offset:23552
	global_load_lds_dwordx4 v[212:213], off
	v_lshl_add_u64 v[214:215], s[44:45], 0, v[132:133]
	s_mov_b32 m0, s64
	s_nop 0
	global_load_lds_dwordx4 v[214:215], off
	s_add_u32 s22, s42, 0x158000
	s_addc_u32 s23, s43, 0
	s_add_i32 s51, s60, s48
	v_lshl_add_u64 v[232:233], s[22:23], 0, v[0:1]
	s_mov_b32 m0, s51
	s_nop 0
	global_load_lds_dwordx4 v[232:233], off
	v_lshl_add_u64 v[232:233], s[22:23], 0, v[134:135]
	s_add_i32 m0, s51, 0x2000
	s_nop 0
	global_load_lds_dwordx4 v[232:233], off
	s_waitcnt vmcnt(40) lgkmcnt(0)
	s_barrier
; #define PG8_STAGE(bufoff, gbase, voff) do { _Pragma("unroll") for (int _i = 0; _i < 2; ++_i) \
;         __builtin_amdgcn_global_load_lds((const unsigned*)((const char*)(gbase) + (voff)[_i]), (LAS unsigned*)(lds + (bufoff) + ldsw + _i * 8192), 16, 0, 0); } while (0)
; #define PG8_LDA(dst, b, h) do { _Pragma("unroll") for (int m = 0; m < 4; ++m) _Pragma("unroll") for (int k = 0; k < 2; ++k) dst[m][k] = *(const LAS h16x8*)(lds + PG8_SA(b, h) + aoff + m * 2048 + k * 1024); } while (0)
; #define PG8_LDB(dst, b, h) do { _Pragma("unroll") for (int n = 0; n < 2; ++n) _Pragma("unroll") for (int k = 0; k < 2; ++k) dst[n][k] = *(const LAS h16x8*)(lds + PG8_SB(b, h) + boff + n * 2048 + k * 1024); } while (0)
; #define PG8_MMA(ai, bj, At, Bt_) do { __builtin_amdgcn_s_setprio(1); _Pragma("unroll") for (int m = 0; m < 4; ++m) _Pragma("unroll") for (int n = 0; n < 2; ++n) _Pragma("unroll") for (int k = 0; k < 2; ++k) \
;         acc[ai][bj][m][n] = __builtin_amdgcn_mfma_f32_16x16x32_f16(Bt_[n][k], At[m][k], acc[ai][bj][m][n], 0, 0, 0); __builtin_amdgcn_s_setprio(0); } while (0)
; #define PG8_WAIT_V(n) asm volatile("s_waitcnt vmcnt(" #n ")" ::: "memory")
; #define PG8_WAIT_L(n) asm volatile("s_waitcnt lgkmcnt(" #n ")" ::: "memory")
; #define PG8_BAR __builtin_amdgcn_s_barrier()
; #define PG8_SCHED __builtin_amdgcn_sched_barrier(0)
; template <class Epi, class AMap>
; __device__ __forceinline__ void gemm_phase(LAS unsigned char* lds, const AMap am, const int lda, const h16* Bt, const int ldb, const int M, const int N, const int K, const Epi& E) {
;     ...
;             PG8_WAIT_V(6); PG8_BAR; PG8_MMA(1, 1, At, B1); PG8_BAR;
;             PG8_LDB(B0, 1, 0); PG8_SCHED; PG8_LDA(At, 1, 0); PG8_STAGE(PG8_SA(0, 1), a2 + hstepA, voffA);
;             PG8_WAIT_L(8); PG8_BAR; PG8_WAIT_L(0); PG8_MMA(0, 0, At, B0); PG8_BAR; PG8_SCHED;
;             PG8_LDB(B1, 1, 1); PG8_STAGE(PG8_SB(1, 0), b3, voffB);
;             PG8_BAR; PG8_WAIT_L(0); PG8_MMA(0, 1, At, B1); PG8_BAR;
	v_mfma_f32_16x16x32_f16 v[62:65], v[140:143], v[162:165], 0
	v_mfma_f32_16x16x32_f16 v[58:61], v[154:157], v[162:165], 0
	v_mfma_f32_16x16x32_f16 v[46:49], v[140:143], v[170:173], 0
	v_mfma_f32_16x16x32_f16 v[42:45], v[154:157], v[170:173], 0
	v_mfma_f32_16x16x32_f16 v[30:33], v[140:143], v[178:181], 0
	v_mfma_f32_16x16x32_f16 v[26:29], v[154:157], v[178:181], 0
	v_mfma_f32_16x16x32_f16 v[14:17], v[140:143], v[186:189], 0
	v_mfma_f32_16x16x32_f16 v[10:13], v[154:157], v[186:189], 0
	v_mfma_f32_16x16x32_f16 v[62:65], v[150:153], v[166:169], v[62:65]
	v_mfma_f32_16x16x32_f16 v[58:61], v[158:161], v[166:169], v[58:61]
	v_mfma_f32_16x16x32_f16 v[46:49], v[150:153], v[174:177], v[46:49]
	v_mfma_f32_16x16x32_f16 v[42:45], v[158:161], v[174:177], v[42:45]
	v_mfma_f32_16x16x32_f16 v[30:33], v[150:153], v[182:185], v[30:33]
	v_mfma_f32_16x16x32_f16 v[26:29], v[158:161], v[182:185], v[26:29]
	v_mfma_f32_16x16x32_f16 v[14:17], v[150:153], v[190:193], v[14:17]
	v_mfma_f32_16x16x32_f16 v[10:13], v[158:161], v[190:193], v[10:13]
	v_mfma_f32_16x16x32_f16 v[54:57], v[194:197], v[162:165], 0
	v_mfma_f32_16x16x32_f16 v[50:53], v[202:205], v[162:165], 0
	v_mfma_f32_16x16x32_f16 v[38:41], v[194:197], v[170:173], 0
	v_mfma_f32_16x16x32_f16 v[34:37], v[202:205], v[170:173], 0
	v_mfma_f32_16x16x32_f16 v[22:25], v[194:197], v[178:181], 0
	v_mfma_f32_16x16x32_f16 v[18:21], v[202:205], v[178:181], 0
	v_mfma_f32_16x16x32_f16 v[6:9], v[194:197], v[186:189], 0
	v_mfma_f32_16x16x32_f16 v[2:5], v[202:205], v[186:189], 0
	v_mfma_f32_16x16x32_f16 v[54:57], v[198:201], v[166:169], v[54:57]
	v_mfma_f32_16x16x32_f16 v[50:53], v[220:223], v[166:169], v[50:53]
	v_mfma_f32_16x16x32_f16 v[38:41], v[198:201], v[174:177], v[38:41]
	v_mfma_f32_16x16x32_f16 v[34:37], v[220:223], v[174:177], v[34:37]
	v_mfma_f32_16x16x32_f16 v[22:25], v[198:201], v[182:185], v[22:25]
	v_mfma_f32_16x16x32_f16 v[18:21], v[220:223], v[182:185], v[18:21]
	v_mfma_f32_16x16x32_f16 v[6:9], v[198:201], v[190:193], v[6:9]
	v_mfma_f32_16x16x32_f16 v[2:5], v[220:223], v[190:193], v[2:5]
	s_barrier
	s_add_i32 s51, 0, 0x18000
	v_add_u32_e32 v234, s51, v147
	ds_read_b128 v[140:143], v234
	ds_read_b128 v[150:153], v234 offset:1024
	ds_read_b128 v[154:157], v234 offset:2048
	ds_read_b128 v[158:161], v234 offset:3072
	s_add_u32 s22, s44, 0x158000
	s_addc_u32 s23, s45, 0
	s_mov_b32 m0, s65
	v_lshl_add_u64 v[232:233], s[22:23], 0, v[130:131]
	ds_read_b128 v[162:165], v149 offset:32768
	ds_read_b128 v[166:169], v149 offset:33792
	ds_read_b128 v[170:173], v149 offset:34816
	ds_read_b128 v[174:177], v149 offset:35840
	ds_read_b128 v[178:181], v149 offset:36864
	ds_read_b128 v[182:185], v149 offset:37888
	ds_read_b128 v[186:189], v149 offset:38912
	ds_read_b128 v[190:193], v149 offset:39936
	global_load_lds_dwordx4 v[232:233], off
	v_lshl_add_u64 v[232:233], s[22:23], 0, v[132:133]
	s_mov_b32 m0, s68
	s_nop 0
	global_load_lds_dwordx4 v[232:233], off
	s_waitcnt lgkmcnt(11)
	s_add_i32 s44, 0, 0x1c000
	s_add_i32 s22, s51, s48
	v_add_u32_e32 v216, s44, v147
	v_lshl_add_u64 v[144:145], v[144:145], 0, s[92:93]
	s_mov_b32 m0, s22
	ds_read_b128 v[194:197], v216
	ds_read_b128 v[198:201], v216 offset:1024
	ds_read_b128 v[202:205], v216 offset:2048
	ds_read_b128 v[220:223], v216 offset:3072
	s_waitcnt vmcnt(8) lgkmcnt(0)
	s_barrier
	v_mfma_f32_16x16x32_f16 v[126:129], v[140:143], v[162:165], v[126:129]
	v_mfma_f32_16x16x32_f16 v[122:125], v[154:157], v[162:165], v[122:125]
	v_mfma_f32_16x16x32_f16 v[110:113], v[140:143], v[170:173], v[110:113]
	v_mfma_f32_16x16x32_f16 v[106:109], v[154:157], v[170:173], v[106:109]
	v_mfma_f32_16x16x32_f16 v[94:97], v[140:143], v[178:181], v[94:97]
	v_mfma_f32_16x16x32_f16 v[90:93], v[154:157], v[178:181], v[90:93]
	v_mfma_f32_16x16x32_f16 v[78:81], v[140:143], v[186:189], v[78:81]
	v_mfma_f32_16x16x32_f16 v[74:77], v[154:157], v[186:189], v[74:77]
	v_mfma_f32_16x16x32_f16 v[126:129], v[150:153], v[166:169], v[126:129]
	v_mfma_f32_16x16x32_f16 v[122:125], v[158:161], v[166:169], v[122:125]
	v_mfma_f32_16x16x32_f16 v[110:113], v[150:153], v[174:177], v[110:113]
	v_mfma_f32_16x16x32_f16 v[106:109], v[158:161], v[174:177], v[106:109]
	v_mfma_f32_16x16x32_f16 v[94:97], v[150:153], v[182:185], v[94:97]
	v_mfma_f32_16x16x32_f16 v[90:93], v[158:161], v[182:185], v[90:93]
	v_mfma_f32_16x16x32_f16 v[78:81], v[150:153], v[190:193], v[78:81]
	v_mfma_f32_16x16x32_f16 v[74:77], v[158:161], v[190:193], v[74:77]
	v_mfma_f32_16x16x32_f16 v[118:121], v[194:197], v[162:165], v[118:121]
	v_mfma_f32_16x16x32_f16 v[114:117], v[202:205], v[162:165], v[114:117]
	v_mfma_f32_16x16x32_f16 v[102:105], v[194:197], v[170:173], v[102:105]
	v_mfma_f32_16x16x32_f16 v[98:101], v[202:205], v[170:173], v[98:101]
	v_mfma_f32_16x16x32_f16 v[86:89], v[194:197], v[178:181], v[86:89]
	v_mfma_f32_16x16x32_f16 v[82:85], v[202:205], v[178:181], v[82:85]
	v_mfma_f32_16x16x32_f16 v[70:73], v[194:197], v[186:189], v[70:73]
	v_mfma_f32_16x16x32_f16 v[66:69], v[202:205], v[186:189], v[66:69]
	v_mfma_f32_16x16x32_f16 v[118:121], v[198:201], v[166:169], v[118:121]
	v_mfma_f32_16x16x32_f16 v[114:117], v[220:223], v[166:169], v[114:117]
	v_mfma_f32_16x16x32_f16 v[102:105], v[198:201], v[174:177], v[102:105]
	v_mfma_f32_16x16x32_f16 v[98:101], v[220:223], v[174:177], v[98:101]
	v_mfma_f32_16x16x32_f16 v[86:89], v[198:201], v[182:185], v[86:89]
	v_mfma_f32_16x16x32_f16 v[82:85], v[220:223], v[182:185], v[82:85]
	v_mfma_f32_16x16x32_f16 v[70:73], v[198:201], v[190:193], v[70:73]
	v_mfma_f32_16x16x32_f16 v[66:69], v[220:223], v[190:193], v[66:69]
	s_barrier
; #define PG8_STAGE(bufoff, gbase, voff) do { _Pragma("unroll") for (int _i = 0; _i < 2; ++_i) \
;         __builtin_amdgcn_global_load_lds((const unsigned*)((const char*)(gbase) + (voff)[_i]), (LAS unsigned*)(lds + (bufoff) + ldsw + _i * 8192), 16, 0, 0); } while (0)
; #define PG8_LDA(dst, b, h) do { _Pragma("unroll") for (int m = 0; m < 4; ++m) _Pragma("unroll") for (int k = 0; k < 2; ++k) dst[m][k] = *(const LAS h16x8*)(lds + PG8_SA(b, h) + aoff + m * 2048 + k * 1024); } while (0)
; #define PG8_MMA(ai, bj, At, Bt_) do { __builtin_amdgcn_s_setprio(1); _Pragma("unroll") for (int m = 0; m < 4; ++m) _Pragma("unroll") for (int n = 0; n < 2; ++n) _Pragma("unroll") for (int k = 0; k < 2; ++k) \
;         acc[ai][bj][m][n] = __builtin_amdgcn_mfma_f32_16x16x32_f16(Bt_[n][k], At[m][k], acc[ai][bj][m][n], 0, 0, 0); __builtin_amdgcn_s_setprio(0); } while (0)
; #define PG8_WAIT_V(n) asm volatile("s_waitcnt vmcnt(" #n ")" ::: "memory")
; #define PG8_WAIT_L(n) asm volatile("s_waitcnt lgkmcnt(" #n ")" ::: "memory")
; #define PG8_BAR __builtin_amdgcn_s_barrier()
; #define PG8_SCHED __builtin_amdgcn_sched_barrier(0)
; template <class Epi, class AMap>
; __device__ __forceinline__ void gemm_phase(LAS unsigned char* lds, const AMap am, const int lda, const h16* Bt, const int ldb, const int M, const int N, const int K, const Epi& E) {
;     ...
;             PG8_LDA(At, 1, 1); PG8_STAGE(PG8_SA(1, 0), a3, voffA);
;             PG8_BAR; PG8_WAIT_L(0); PG8_MMA(1, 0, At, B0); PG8_BAR; PG8_SCHED;
;             PG8_STAGE(PG8_SB(1, 1), b3 + hstepB, voffB);
;             PG8_WAIT_V(6); PG8_BAR; PG8_MMA(1, 1, At, B1); PG8_BAR;
;         }
	global_load_lds_dwordx4 v[144:145], off
	v_lshl_add_u64 v[144:145], v[206:207], 0, s[92:93]
	s_add_i32 m0, s22, 0x2000
	s_nop 0
	global_load_lds_dwordx4 v[144:145], off
	s_mov_b32 m0, s69
	v_lshl_add_u64 v[144:145], v[212:213], 0, s[92:93]
	ds_read_b128 v[162:165], v149 offset:49152
	ds_read_b128 v[166:169], v149 offset:50176
	ds_read_b128 v[170:173], v149 offset:51200
	ds_read_b128 v[174:177], v149 offset:52224
	ds_read_b128 v[178:181], v149 offset:53248
	ds_read_b128 v[182:185], v149 offset:54272
	ds_read_b128 v[186:189], v149 offset:55296
	ds_read_b128 v[190:193], v149 offset:56320
	global_load_lds_dwordx4 v[144:145], off
	v_lshl_add_u64 v[144:145], v[214:215], 0, s[92:93]
	s_mov_b32 m0, s70
	s_nop 0
	global_load_lds_dwordx4 v[144:145], off
	s_add_u32 s22, s42, 0x158080
	s_addc_u32 s23, s43, 0
	s_add_i32 s42, s44, s48
	v_lshl_add_u64 v[232:233], s[22:23], 0, v[0:1]
	s_mov_b32 m0, s42
	s_nop 0
	global_load_lds_dwordx4 v[232:233], off
	v_lshl_add_u64 v[232:233], s[22:23], 0, v[134:135]
	s_add_i32 m0, s42, 0x2000
	s_nop 0
	global_load_lds_dwordx4 v[232:233], off
	s_add_i32 s29, s29, 2
	s_add_u32 s20, s20, 0x100
	s_addc_u32 s21, s21, 0
	s_cmpk_gt_u32 s29, 0x53
	s_mov_b64 s[22:23], s[26:27]
	s_waitcnt vmcnt(8) lgkmcnt(0)
	s_barrier
	v_mfma_f32_16x16x32_f16 v[62:65], v[140:143], v[162:165], v[62:65]
	v_mfma_f32_16x16x32_f16 v[58:61], v[154:157], v[162:165], v[58:61]
	v_mfma_f32_16x16x32_f16 v[46:49], v[140:143], v[170:173], v[46:49]
	v_mfma_f32_16x16x32_f16 v[42:45], v[154:157], v[170:173], v[42:45]
	v_mfma_f32_16x16x32_f16 v[30:33], v[140:143], v[178:181], v[30:33]
	v_mfma_f32_16x16x32_f16 v[26:29], v[154:157], v[178:181], v[26:29]
	v_mfma_f32_16x16x32_f16 v[14:17], v[140:143], v[186:189], v[14:17]
	v_mfma_f32_16x16x32_f16 v[10:13], v[154:157], v[186:189], v[10:13]
	v_mfma_f32_16x16x32_f16 v[62:65], v[150:153], v[166:169], v[62:65]
	v_mfma_f32_16x16x32_f16 v[58:61], v[158:161], v[166:169], v[58:61]
	v_mfma_f32_16x16x32_f16 v[46:49], v[150:153], v[174:177], v[46:49]
	v_mfma_f32_16x16x32_f16 v[42:45], v[158:161], v[174:177], v[42:45]
	v_mfma_f32_16x16x32_f16 v[30:33], v[150:153], v[182:185], v[30:33]
	v_mfma_f32_16x16x32_f16 v[26:29], v[158:161], v[182:185], v[26:29]
	v_mfma_f32_16x16x32_f16 v[14:17], v[150:153], v[190:193], v[14:17]
	v_mfma_f32_16x16x32_f16 v[10:13], v[158:161], v[190:193], v[10:13]
	v_mfma_f32_16x16x32_f16 v[54:57], v[194:197], v[162:165], v[54:57]
	v_mfma_f32_16x16x32_f16 v[50:53], v[202:205], v[162:165], v[50:53]
	v_mfma_f32_16x16x32_f16 v[38:41], v[194:197], v[170:173], v[38:41]
	v_mfma_f32_16x16x32_f16 v[34:37], v[202:205], v[170:173], v[34:37]
	v_mfma_f32_16x16x32_f16 v[22:25], v[194:197], v[178:181], v[22:25]
	v_mfma_f32_16x16x32_f16 v[18:21], v[202:205], v[178:181], v[18:21]
	v_mfma_f32_16x16x32_f16 v[6:9], v[194:197], v[186:189], v[6:9]
	v_mfma_f32_16x16x32_f16 v[2:5], v[202:205], v[186:189], v[2:5]
	v_mfma_f32_16x16x32_f16 v[54:57], v[198:201], v[166:169], v[54:57]
	v_mfma_f32_16x16x32_f16 v[50:53], v[220:223], v[166:169], v[50:53]
	v_mfma_f32_16x16x32_f16 v[38:41], v[198:201], v[174:177], v[38:41]
	v_mfma_f32_16x16x32_f16 v[34:37], v[220:223], v[174:177], v[34:37]
	v_mfma_f32_16x16x32_f16 v[22:25], v[198:201], v[182:185], v[22:25]
	v_mfma_f32_16x16x32_f16 v[18:21], v[220:223], v[182:185], v[18:21]
	v_mfma_f32_16x16x32_f16 v[6:9], v[198:201], v[190:193], v[6:9]
	v_mfma_f32_16x16x32_f16 v[2:5], v[220:223], v[190:193], v[2:5]
	s_barrier
	s_cbranch_scc1 .Lg4x_61

; template <int CTRL> __device__ __forceinline__ float dpp_f(float x) { return __int_as_float(__builtin_amdgcn_update_dpp(0, __float_as_int(x), CTRL, 0xF, 0xF, true)); }
; #define PG8_STAGE(bufoff, gbase, voff) do { _Pragma("unroll") for (int _i = 0; _i < 2; ++_i) \
;         __builtin_amdgcn_global_load_lds((const unsigned*)((const char*)(gbase) + (voff)[_i]), (LAS unsigned*)(lds + (bufoff) + ldsw + _i * 8192), 16, 0, 0); } while (0)
; #define PG8_WAIT_V(n) asm volatile("s_waitcnt vmcnt(" #n ")" ::: "memory")
; #define PG8_BAR __builtin_amdgcn_s_barrier()
; template <class Epi, class AMap>
; __device__ __forceinline__ void gemm_phase(LAS unsigned char* lds, const AMap am, const int lda, const h16* Bt, const int ldb, const int M, const int N, const int K, const Epi& E) {
;     ...
;     PG8_STAGE(PG8_SB(0, 0), cB, voffB); PG8_STAGE(PG8_SA(0, 0), cA, voffA); PG8_STAGE(PG8_SB(0, 1), cB + hstepB, voffB); PG8_STAGE(PG8_SA(0, 1), cA + hstepA, voffA);
;     if (wr == 1) PG8_BAR;
;     PG8_WAIT_V(4); PG8_BAR;
;     PG8_STAGE(PG8_SB(1, 0), cB + kstep, voffB); PG8_STAGE(PG8_SA(1, 0), cA + kstep, voffA); PG8_STAGE(PG8_SB(1, 1), cB + hstepB + kstep, voffB);
;     PG8_WAIT_V(6); PG8_BAR;
;     __device__ __forceinline__ void operator()(const f32x4 (&acc)[2][2][4][2], const Unit& u, int wr, int wc, int fr, int fq) const {
;     ...
;                         const float g = acc[ai][1][m][n][e];
;                         r1[n][e] = dpp_f<0x121>(g); r2[n][e] = dpp_f<0x122>(g);
;                         const float g1 = fr >= 1 ? r1[n][e] : p1[n][e], g2 = fr >= 2 ? r2[n][e] : p2[n][e];
;                         const float gc = bb[n][e] + g2 * w0[n][e] + g1 * w1[n][e] + g * w2[n][e];
;                         o[n][e] = gelu_mul(acc[ai][0][m][n][e], gc);
;                     }
;                 if (m > 0 || fr >= 2) *(u32x4*)(ACT + (size_t)row * FF + f0) = pack8(o[0], o[1]);
;                 if (m == 0 && fr < 2) { h16* sp = SIDE + ((size_t)(row >> 6) * 4 + 2 + fr) * (2 * FF) + f0;
;                     *(u32x4*)sp = pack8(acc[ai][0][m][0], acc[ai][0][m][1]); *(u32x4*)(sp + FF) = pack8(acc[ai][1][m][0], acc[ai][1][m][1]); }
;                 if (m == 3 && fr >= 14) { h16* sp = SIDE + ((size_t)(row >> 6) * 4 + (fr - 14)) * (2 * FF) + FF + f0;
.LBB0_87:
	s_lshl_b32 s0, s0, 5
	s_and_b32 s0, s0, 0x60
	s_lshl_b32 s51, s1, 6
	s_lshl_b32 s1, s1, 13
	s_lshl_b32 s29, s0, 7
	s_add_u32 s8, s74, 0x5600
	s_addc_u32 s9, s75, 0
	s_add_u32 s70, s74, 0xac00
	s_addc_u32 s71, s75, 0
	s_add_i32 m0, s81, 0x18000
	v_lshl_add_u64 v[8:9], v[8:9], 0, s[92:93]
	s_waitcnt vmcnt(0)
	s_barrier
	global_load_lds_dwordx4 v[8:9], off
	v_lshl_add_u64 v[6:7], v[6:7], 0, s[92:93]
	s_add_i32 m0, s81, 0x1a000
	s_add_i32 s89, s81, 0x8000
	s_add_i32 s35, s81, 0xa000
	global_load_lds_dwordx4 v[6:7], off
	v_lshl_add_u64 v[4:5], v[4:5], 0, s[92:93]
	s_mov_b32 m0, s89
	s_add_u32 s20, s48, 0x80080
	global_load_lds_dwordx4 v[4:5], off
	v_lshl_add_u64 v[2:3], v[2:3], 0, s[92:93]
	s_mov_b32 m0, s35
	s_addc_u32 s21, s49, 0
	global_load_lds_dwordx4 v[2:3], off
	s_add_i32 m0, s81, 0x1c000
	v_lshl_add_u64 v[2:3], s[20:21], 0, v[0:1]
	global_load_lds_dwordx4 v[2:3], off
	v_lshl_add_u64 v[2:3], s[20:21], 0, v[162:163]
	s_add_i32 m0, s81, 0x1e000
	v_and_b32_e32 v168, 15, v10
	global_load_lds_dwordx4 v[2:3], off
	v_lshrrev_b32_e32 v2, 1, v10
	v_and_b32_e32 v2, 24, v2
	v_lshlrev_b32_e32 v3, 1, v2
	v_lshlrev_b32_e32 v4, 2, v10
	v_or_b32_e32 v194, s0, v2
	v_lshlrev_b32_e32 v2, 15, v15
	v_lshl_or_b32 v3, v168, 6, v3
	v_and_b32_e32 v4, 32, v4
	v_and_b32_e32 v2, 0xffff0000, v2
	v_bitop3_b32 v5, v3, s1, v4 bitop3:0xde
	v_bitop3_b32 v169, v3, s29, v4 bitop3:0xde
	v_lshl_add_u32 v2, v14, 12, v2
	v_and_b32_e32 v3, 1, v15
	v_lshl_or_b32 v2, v3, 6, v2
	v_lshl_add_u32 v172, v16, 1, v2
	v_lshlrev_b32_e32 v2, 15, v11
	v_and_b32_e32 v2, 0xffff0000, v2
	s_waitcnt vmcnt(0)
	v_lshl_add_u32 v2, v12, 12, v2
	v_and_b32_e32 v3, 1, v11
	v_lshl_or_b32 v2, v3, 6, v2
	s_sext_i32_i16 s23, s24
	s_mov_b32 s24, 0
	v_cmp_eq_u32_e64 s[38:39], 0, v168
	v_cmp_lt_u32_e64 s[40:41], 1, v168
	v_cmp_gt_u32_e64 s[42:43], 2, v168
	v_cmp_lt_u32_e64 s[44:45], 13, v168
	v_add_u32_e32 v170, -14, v168
	v_mov_b32_e32 v171, v1
	v_mov_b32_e32 v173, v1
	v_lshl_add_u32 v174, v13, 1, v2
	v_mov_b32_e32 v175, v1
	v_add_u32_e32 v195, 0, v5
	s_barrier
	s_branch .LBB0_89

; #define PG8_STAGE(bufoff, gbase, voff) do { _Pragma("unroll") for (int _i = 0; _i < 2; ++_i) \
;         __builtin_amdgcn_global_load_lds((const unsigned*)((const char*)(gbase) + (voff)[_i]), (LAS unsigned*)(lds + (bufoff) + ldsw + _i * 8192), 16, 0, 0); } while (0)
; #define PG8_LDA(dst, b, h) do { _Pragma("unroll") for (int m = 0; m < 4; ++m) _Pragma("unroll") for (int k = 0; k < 2; ++k) dst[m][k] = *(const LAS h16x8*)(lds + PG8_SA(b, h) + aoff + m * 2048 + k * 1024); } while (0)
; #define PG8_LDB(dst, b, h) do { _Pragma("unroll") for (int n = 0; n < 2; ++n) _Pragma("unroll") for (int k = 0; k < 2; ++k) dst[n][k] = *(const LAS h16x8*)(lds + PG8_SB(b, h) + boff + n * 2048 + k * 1024); } while (0)
; #define PG8_MMA(ai, bj, At, Bt_) do { __builtin_amdgcn_s_setprio(1); _Pragma("unroll") for (int m = 0; m < 4; ++m) _Pragma("unroll") for (int n = 0; n < 2; ++n) _Pragma("unroll") for (int k = 0; k < 2; ++k) \
;         acc[ai][bj][m][n] = __builtin_amdgcn_mfma_f32_16x16x32_f16(Bt_[n][k], At[m][k], acc[ai][bj][m][n], 0, 0, 0); __builtin_amdgcn_s_setprio(0); } while (0)
; #define PG8_WAIT_V(n) asm volatile("s_waitcnt vmcnt(" #n ")" ::: "memory")
; #define PG8_WAIT_L(n) asm volatile("s_waitcnt lgkmcnt(" #n ")" ::: "memory")
; template <class Epi, class AMap>
; __device__ __forceinline__ void gemm_phase(LAS unsigned char* lds, const AMap am, const int lda, const h16* Bt, const int ldb, const int M, const int N, const int K, const Epi& E) {
;     ...
;             const bool last = (t == nt - 2);
;             const char* a1 = cA + (size_t)(t + 1) * kstep;
;             const char* a2 = last ? nA : cA + (size_t)(t + 2) * kstep; const char* b2 = last ? nB : cB + (size_t)(t + 2) * kstep;
;             const char* a3 = a2 + kstep; const char* b3 = b2 + kstep;
;             PG8_LDB(B0, 0, 0); PG8_SCHED; PG8_LDA(At, 0, 0); PG8_STAGE(PG8_SA(1, 1), a1 + hstepA, voffA);
;             PG8_WAIT_L(8); PG8_BAR; PG8_WAIT_L(0); PG8_MMA(0, 0, At, B0); PG8_BAR; PG8_SCHED;
;             PG8_LDB(B1, 0, 1); PG8_STAGE(PG8_SB(0, 0), b2, voffB);
;             PG8_BAR; PG8_WAIT_L(0); PG8_MMA(0, 1, At, B1); PG8_BAR;
;             PG8_LDA(At, 0, 1); PG8_STAGE(PG8_SA(0, 0), a2, voffA);
;             PG8_BAR; PG8_WAIT_L(0); PG8_MMA(1, 0, At, B0); PG8_BAR; PG8_SCHED;
;             PG8_STAGE(PG8_SB(0, 1), b2 + hstepB, voffB);
;             PG8_WAIT_V(6); PG8_BAR; PG8_MMA(1, 1, At, B1); PG8_BAR;
.Lg4p_92:
	s_add_u32 s0, vcc_lo, 0xfff80080
	s_addc_u32 s1, vcc_hi, -1
	s_add_i32 s67, 0, 0x10000
	v_add_u32_e32 v226, s67, v169
	ds_read_b128 v[66:69], v226
	ds_read_b128 v[70:73], v226 offset:1024
	ds_read_b128 v[74:77], v226 offset:2048
	ds_read_b128 v[78:81], v226 offset:3072
	s_cmp_eq_u32 s60, 28
	s_cselect_b32 s27, s69, s1
	s_cselect_b32 s26, s29, s0
	s_cselect_b32 s49, s73, s66
	s_cselect_b32 s48, s20, s21
	v_lshl_add_u64 v[192:193], vcc, 0, v[172:173]
	s_add_i32 m0, s81, 0xc000
	ds_read_b128 v[90:93], v195
	ds_read_b128 v[94:97], v195 offset:1024
	ds_read_b128 v[98:101], v195 offset:2048
	ds_read_b128 v[102:105], v195 offset:3072
	ds_read_b128 v[176:179], v195 offset:4096
	ds_read_b128 v[180:183], v195 offset:5120
	ds_read_b128 v[184:187], v195 offset:6144
	ds_read_b128 v[188:191], v195 offset:7168
	global_load_lds_dwordx4 v[192:193], off
	v_lshl_add_u64 v[192:193], vcc, 0, v[174:175]
	s_add_i32 m0, s81, 0xe000
	s_nop 0
	global_load_lds_dwordx4 v[192:193], off
	s_waitcnt lgkmcnt(11)
	s_add_i32 s65, 0, 0x14000
	v_add_u32_e32 v192, s65, v169
	s_add_i32 s0, s67, s64
	ds_read_b128 v[196:199], v192
	ds_read_b128 v[200:203], v192 offset:1024
	ds_read_b128 v[204:207], v192 offset:2048
	ds_read_b128 v[220:223], v192 offset:3072
	s_waitcnt vmcnt(22) lgkmcnt(0)
	s_barrier
	v_mfma_f32_16x16x32_f16 v[158:161], v[66:69], v[90:93], 0
	v_mfma_f32_16x16x32_f16 v[154:157], v[74:77], v[90:93], 0
	v_mfma_f32_16x16x32_f16 v[142:145], v[66:69], v[98:101], 0
	v_mfma_f32_16x16x32_f16 v[134:137], v[74:77], v[98:101], 0
	v_mfma_f32_16x16x32_f16 v[126:129], v[66:69], v[176:179], 0
	v_mfma_f32_16x16x32_f16 v[118:121], v[74:77], v[176:179], 0
	v_mfma_f32_16x16x32_f16 v[110:113], v[66:69], v[184:187], 0
	v_mfma_f32_16x16x32_f16 v[106:109], v[74:77], v[184:187], 0
	v_mfma_f32_16x16x32_f16 v[158:161], v[70:73], v[94:97], v[158:161]
	v_mfma_f32_16x16x32_f16 v[154:157], v[78:81], v[94:97], v[154:157]
	v_mfma_f32_16x16x32_f16 v[142:145], v[70:73], v[102:105], v[142:145]
	v_mfma_f32_16x16x32_f16 v[134:137], v[78:81], v[102:105], v[134:137]
	v_mfma_f32_16x16x32_f16 v[126:129], v[70:73], v[180:183], v[126:129]
	v_mfma_f32_16x16x32_f16 v[118:121], v[78:81], v[180:183], v[118:121]
	v_mfma_f32_16x16x32_f16 v[110:113], v[70:73], v[188:191], v[110:113]
	v_mfma_f32_16x16x32_f16 v[106:109], v[78:81], v[188:191], v[106:109]
	v_mfma_f32_16x16x32_f16 v[150:153], v[196:199], v[90:93], 0
	v_mfma_f32_16x16x32_f16 v[146:149], v[204:207], v[90:93], 0
	v_mfma_f32_16x16x32_f16 v[150:153], v[200:203], v[94:97], v[150:153]
	v_mfma_f32_16x16x32_f16 v[146:149], v[220:223], v[94:97], v[146:149]
	v_mfma_f32_16x16x32_f16 v[138:141], v[196:199], v[98:101], 0
	v_mfma_f32_16x16x32_f16 v[130:133], v[204:207], v[98:101], 0
	v_mfma_f32_16x16x32_f16 v[114:117], v[204:207], v[176:179], 0
	v_mfma_f32_16x16x32_f16 v[86:89], v[196:199], v[184:187], 0
	v_mfma_f32_16x16x32_f16 v[82:85], v[204:207], v[184:187], 0
	v_mfma_f32_16x16x32_f16 v[138:141], v[200:203], v[102:105], v[138:141]
	v_mfma_f32_16x16x32_f16 v[130:133], v[220:223], v[102:105], v[130:133]
	v_mfma_f32_16x16x32_f16 v[122:125], v[196:199], v[176:179], 0
	v_mfma_f32_16x16x32_f16 v[114:117], v[220:223], v[180:183], v[114:117]
	v_mfma_f32_16x16x32_f16 v[86:89], v[200:203], v[188:191], v[86:89]
	v_mfma_f32_16x16x32_f16 v[82:85], v[220:223], v[188:191], v[82:85]
	v_mfma_f32_16x16x32_f16 v[122:125], v[200:203], v[180:183], v[122:125]
	s_barrier
	v_lshl_add_u64 v[192:193], s[48:49], 0, v[0:1]
	s_mov_b32 m0, s0
	v_lshl_add_u64 v[212:213], s[48:49], 0, v[162:163]
	global_load_lds_dwordx4 v[192:193], off
	s_add_i32 m0, s0, 0x2000
	s_nop 0
	global_load_lds_dwordx4 v[212:213], off
	s_mov_b32 m0, s81
	v_lshl_add_u64 v[214:215], s[26:27], 0, v[166:167]
	ds_read_b128 v[90:93], v195 offset:16384
	ds_read_b128 v[94:97], v195 offset:17408
	ds_read_b128 v[98:101], v195 offset:18432
	ds_read_b128 v[102:105], v195 offset:19456
	ds_read_b128 v[176:179], v195 offset:20480
	ds_read_b128 v[180:183], v195 offset:21504
	ds_read_b128 v[184:187], v195 offset:22528
	ds_read_b128 v[188:191], v195 offset:23552
	global_load_lds_dwordx4 v[214:215], off
	v_lshl_add_u64 v[216:217], s[26:27], 0, v[164:165]
	s_mov_b32 m0, s82
	s_nop 0
	global_load_lds_dwordx4 v[216:217], off
	s_add_u32 s0, s48, 0x80000
	s_addc_u32 s1, s49, 0
	s_add_i32 s65, s65, s64
	v_lshl_add_u64 v[224:225], s[0:1], 0, v[0:1]
	s_mov_b32 m0, s65
	s_nop 0
	global_load_lds_dwordx4 v[224:225], off
	v_lshl_add_u64 v[224:225], s[0:1], 0, v[162:163]
	s_add_i32 m0, s65, 0x2000
	s_nop 0
	global_load_lds_dwordx4 v[224:225], off
	s_waitcnt vmcnt(22) lgkmcnt(0)
	s_barrier
	v_mfma_f32_16x16x32_f16 v[62:65], v[66:69], v[90:93], 0
	v_mfma_f32_16x16x32_f16 v[58:61], v[74:77], v[90:93], 0
	v_mfma_f32_16x16x32_f16 v[46:49], v[66:69], v[98:101], 0
	v_mfma_f32_16x16x32_f16 v[38:41], v[74:77], v[98:101], 0
	v_mfma_f32_16x16x32_f16 v[30:33], v[66:69], v[176:179], 0
	v_mfma_f32_16x16x32_f16 v[22:25], v[74:77], v[176:179], 0
	v_mfma_f32_16x16x32_f16 v[14:17], v[66:69], v[184:187], 0
	v_mfma_f32_16x16x32_f16 v[10:13], v[74:77], v[184:187], 0
	v_mfma_f32_16x16x32_f16 v[62:65], v[70:73], v[94:97], v[62:65]
	v_mfma_f32_16x16x32_f16 v[58:61], v[78:81], v[94:97], v[58:61]
	v_mfma_f32_16x16x32_f16 v[46:49], v[70:73], v[102:105], v[46:49]
	v_mfma_f32_16x16x32_f16 v[38:41], v[78:81], v[102:105], v[38:41]
	v_mfma_f32_16x16x32_f16 v[30:33], v[70:73], v[180:183], v[30:33]
	v_mfma_f32_16x16x32_f16 v[22:25], v[78:81], v[180:183], v[22:25]
	v_mfma_f32_16x16x32_f16 v[14:17], v[70:73], v[188:191], v[14:17]
	v_mfma_f32_16x16x32_f16 v[10:13], v[78:81], v[188:191], v[10:13]
	v_mfma_f32_16x16x32_f16 v[54:57], v[196:199], v[90:93], 0
	v_mfma_f32_16x16x32_f16 v[50:53], v[204:207], v[90:93], 0
	v_mfma_f32_16x16x32_f16 v[42:45], v[196:199], v[98:101], 0
	v_mfma_f32_16x16x32_f16 v[34:37], v[204:207], v[98:101], 0
	v_mfma_f32_16x16x32_f16 v[26:29], v[196:199], v[176:179], 0
	v_mfma_f32_16x16x32_f16 v[18:21], v[204:207], v[176:179], 0
	v_mfma_f32_16x16x32_f16 v[6:9], v[196:199], v[184:187], 0
	v_mfma_f32_16x16x32_f16 v[2:5], v[204:207], v[184:187], 0
	v_mfma_f32_16x16x32_f16 v[54:57], v[200:203], v[94:97], v[54:57]
	v_mfma_f32_16x16x32_f16 v[50:53], v[220:223], v[94:97], v[50:53]
	v_mfma_f32_16x16x32_f16 v[42:45], v[200:203], v[102:105], v[42:45]
	v_mfma_f32_16x16x32_f16 v[34:37], v[220:223], v[102:105], v[34:37]
	v_mfma_f32_16x16x32_f16 v[26:29], v[200:203], v[180:183], v[26:29]
	v_mfma_f32_16x16x32_f16 v[18:21], v[220:223], v[180:183], v[18:21]
	v_mfma_f32_16x16x32_f16 v[6:9], v[200:203], v[188:191], v[6:9]
	v_mfma_f32_16x16x32_f16 v[2:5], v[220:223], v[188:191], v[2:5]
	s_barrier
; #define PG8_STAGE(bufoff, gbase, voff) do { _Pragma("unroll") for (int _i = 0; _i < 2; ++_i) \
;         __builtin_amdgcn_global_load_lds((const unsigned*)((const char*)(gbase) + (voff)[_i]), (LAS unsigned*)(lds + (bufoff) + ldsw + _i * 8192), 16, 0, 0); } while (0)
; #define PG8_LDA(dst, b, h) do { _Pragma("unroll") for (int m = 0; m < 4; ++m) _Pragma("unroll") for (int k = 0; k < 2; ++k) dst[m][k] = *(const LAS h16x8*)(lds + PG8_SA(b, h) + aoff + m * 2048 + k * 1024); } while (0)
; #define PG8_LDB(dst, b, h) do { _Pragma("unroll") for (int n = 0; n < 2; ++n) _Pragma("unroll") for (int k = 0; k < 2; ++k) dst[n][k] = *(const LAS h16x8*)(lds + PG8_SB(b, h) + boff + n * 2048 + k * 1024); } while (0)
; #define PG8_MMA(ai, bj, At, Bt_) do { __builtin_amdgcn_s_setprio(1); _Pragma("unroll") for (int m = 0; m < 4; ++m) _Pragma("unroll") for (int n = 0; n < 2; ++n) _Pragma("unroll") for (int k = 0; k < 2; ++k) \
;         acc[ai][bj][m][n] = __builtin_amdgcn_mfma_f32_16x16x32_f16(Bt_[n][k], At[m][k], acc[ai][bj][m][n], 0, 0, 0); __builtin_amdgcn_s_setprio(0); } while (0)
; #define PG8_WAIT_V(n) asm volatile("s_waitcnt vmcnt(" #n ")" ::: "memory")
; #define PG8_WAIT_L(n) asm volatile("s_waitcnt lgkmcnt(" #n ")" ::: "memory")
; #define PG8_BAR __builtin_amdgcn_s_barrier()
; #define PG8_SCHED __builtin_amdgcn_sched_barrier(0)
; template <class Epi, class AMap>
; __device__ __forceinline__ void gemm_phase(LAS unsigned char* lds, const AMap am, const int lda, const h16* Bt, const int ldb, const int M, const int N, const int K, const Epi& E) {
;     ...
;             PG8_LDB(B0, 1, 0); PG8_SCHED; PG8_LDA(At, 1, 0); PG8_STAGE(PG8_SA(0, 1), a2 + hstepA, voffA);
;             PG8_WAIT_L(8); PG8_BAR; PG8_WAIT_L(0); PG8_MMA(0, 0, At, B0); PG8_BAR; PG8_SCHED;
;             PG8_LDB(B1, 1, 1); PG8_STAGE(PG8_SB(1, 0), b3, voffB);
;             PG8_BAR; PG8_WAIT_L(0); PG8_MMA(0, 1, At, B1); PG8_BAR;
;             PG8_LDA(At, 1, 1); PG8_STAGE(PG8_SA(1, 0), a3, voffA);
;             PG8_BAR; PG8_WAIT_L(0); PG8_MMA(1, 0, At, B0); PG8_BAR; PG8_SCHED;
;             PG8_STAGE(PG8_SB(1, 1), b3 + hstepB, voffB);
;             PG8_WAIT_V(6); PG8_BAR; PG8_MMA(1, 1, At, B1); PG8_BAR;
;         }
	s_add_i32 s65, 0, 0x18000
	v_add_u32_e32 v226, s65, v169
	ds_read_b128 v[66:69], v226
	ds_read_b128 v[70:73], v226 offset:1024
	ds_read_b128 v[74:77], v226 offset:2048
	ds_read_b128 v[78:81], v226 offset:3072
	s_add_u32 s0, s26, 0x80000
	s_addc_u32 s1, s27, 0
	s_mov_b32 m0, s83
	v_lshl_add_u64 v[224:225], s[0:1], 0, v[166:167]
	ds_read_b128 v[90:93], v195 offset:32768
	ds_read_b128 v[94:97], v195 offset:33792
	ds_read_b128 v[98:101], v195 offset:34816
	ds_read_b128 v[102:105], v195 offset:35840
	ds_read_b128 v[176:179], v195 offset:36864
	ds_read_b128 v[180:183], v195 offset:37888
	ds_read_b128 v[184:187], v195 offset:38912
	ds_read_b128 v[188:191], v195 offset:39936
	global_load_lds_dwordx4 v[224:225], off
	v_lshl_add_u64 v[224:225], s[0:1], 0, v[164:165]
	s_mov_b32 m0, s50
	s_nop 0
	global_load_lds_dwordx4 v[224:225], off
	s_waitcnt lgkmcnt(11)
	s_add_i32 s26, 0, 0x1c000
	v_add_u32_e32 v226, s26, v169
	s_add_i32 s0, s65, s64
	ds_read_b128 v[196:199], v226
	ds_read_b128 v[200:203], v226 offset:1024
	ds_read_b128 v[204:207], v226 offset:2048
	ds_read_b128 v[220:223], v226 offset:3072
	s_waitcnt vmcnt(8) lgkmcnt(0)
	s_barrier
	v_mfma_f32_16x16x32_f16 v[158:161], v[66:69], v[90:93], v[158:161]
	v_mfma_f32_16x16x32_f16 v[158:161], v[70:73], v[94:97], v[158:161]
	v_mfma_f32_16x16x32_f16 v[154:157], v[74:77], v[90:93], v[154:157]
	v_mfma_f32_16x16x32_f16 v[154:157], v[78:81], v[94:97], v[154:157]
	v_mfma_f32_16x16x32_f16 v[142:145], v[66:69], v[98:101], v[142:145]
	v_mfma_f32_16x16x32_f16 v[134:137], v[74:77], v[98:101], v[134:137]
	v_mfma_f32_16x16x32_f16 v[126:129], v[66:69], v[176:179], v[126:129]
	v_mfma_f32_16x16x32_f16 v[118:121], v[74:77], v[176:179], v[118:121]
	v_mfma_f32_16x16x32_f16 v[110:113], v[66:69], v[184:187], v[110:113]
	v_mfma_f32_16x16x32_f16 v[106:109], v[74:77], v[184:187], v[106:109]
	v_mfma_f32_16x16x32_f16 v[142:145], v[70:73], v[102:105], v[142:145]
	v_mfma_f32_16x16x32_f16 v[134:137], v[78:81], v[102:105], v[134:137]
	v_mfma_f32_16x16x32_f16 v[126:129], v[70:73], v[180:183], v[126:129]
	v_mfma_f32_16x16x32_f16 v[118:121], v[78:81], v[180:183], v[118:121]
	v_mfma_f32_16x16x32_f16 v[110:113], v[70:73], v[188:191], v[110:113]
	v_mfma_f32_16x16x32_f16 v[106:109], v[78:81], v[188:191], v[106:109]
	v_mfma_f32_16x16x32_f16 v[146:149], v[204:207], v[90:93], v[146:149]
	v_mfma_f32_16x16x32_f16 v[150:153], v[196:199], v[90:93], v[150:153]
	v_mfma_f32_16x16x32_f16 v[146:149], v[220:223], v[94:97], v[146:149]
	v_mfma_f32_16x16x32_f16 v[138:141], v[196:199], v[98:101], v[138:141]
	v_mfma_f32_16x16x32_f16 v[150:153], v[200:203], v[94:97], v[150:153]
	v_mfma_f32_16x16x32_f16 v[138:141], v[200:203], v[102:105], v[138:141]
	v_mfma_f32_16x16x32_f16 v[130:133], v[204:207], v[98:101], v[130:133]
	v_mfma_f32_16x16x32_f16 v[130:133], v[220:223], v[102:105], v[130:133]
	v_mfma_f32_16x16x32_f16 v[122:125], v[196:199], v[176:179], v[122:125]
	v_mfma_f32_16x16x32_f16 v[122:125], v[200:203], v[180:183], v[122:125]
	v_mfma_f32_16x16x32_f16 v[114:117], v[204:207], v[176:179], v[114:117]
	v_mfma_f32_16x16x32_f16 v[86:89], v[196:199], v[184:187], v[86:89]
	v_mfma_f32_16x16x32_f16 v[82:85], v[204:207], v[184:187], v[82:85]
	v_mfma_f32_16x16x32_f16 v[114:117], v[220:223], v[180:183], v[114:117]
	v_mfma_f32_16x16x32_f16 v[86:89], v[200:203], v[188:191], v[86:89]
	v_mfma_f32_16x16x32_f16 v[82:85], v[220:223], v[188:191], v[82:85]
	s_barrier
	v_lshl_add_u64 v[224:225], v[192:193], 0, s[92:93]
	s_mov_b32 m0, s0
	s_nop 0
	global_load_lds_dwordx4 v[224:225], off
	v_lshl_add_u64 v[224:225], v[212:213], 0, s[92:93]
	s_add_i32 m0, s0, 0x2000
	s_nop 0
	global_load_lds_dwordx4 v[224:225], off
	s_mov_b32 m0, s89
	v_lshl_add_u64 v[192:193], v[214:215], 0, s[92:93]
	ds_read_b128 v[90:93], v195 offset:49152
	ds_read_b128 v[94:97], v195 offset:50176
	ds_read_b128 v[98:101], v195 offset:51200
	ds_read_b128 v[102:105], v195 offset:52224
	ds_read_b128 v[176:179], v195 offset:53248
	ds_read_b128 v[180:183], v195 offset:54272
	ds_read_b128 v[184:187], v195 offset:55296
	ds_read_b128 v[188:191], v195 offset:56320
	global_load_lds_dwordx4 v[192:193], off
	v_lshl_add_u64 v[192:193], v[216:217], 0, s[92:93]
	s_mov_b32 m0, s35
	s_nop 0
	global_load_lds_dwordx4 v[192:193], off
	s_add_u32 s0, s48, 0x80080
	s_addc_u32 s1, s49, 0
	s_add_i32 s26, s26, s64
	v_lshl_add_u64 v[224:225], s[0:1], 0, v[0:1]
	s_mov_b32 m0, s26
	s_nop 0
	global_load_lds_dwordx4 v[224:225], off
	v_lshl_add_u64 v[224:225], s[0:1], 0, v[162:163]
	s_add_i32 m0, s26, 0x2000
	s_nop 0
	global_load_lds_dwordx4 v[224:225], off
	s_add_i32 s60, s60, 2
	s_add_u32 vcc_lo, vcc_lo, 0x100
	s_addc_u32 vcc_hi, vcc_hi, 0
	s_add_u32 s21, s21, 0x100
	s_addc_u32 s66, s66, 0
	s_cmp_gt_u32 s60, 29
	s_waitcnt vmcnt(8) lgkmcnt(0)
	s_barrier
	v_mfma_f32_16x16x32_f16 v[62:65], v[66:69], v[90:93], v[62:65]
	v_mfma_f32_16x16x32_f16 v[58:61], v[74:77], v[90:93], v[58:61]
	v_mfma_f32_16x16x32_f16 v[46:49], v[66:69], v[98:101], v[46:49]
	v_mfma_f32_16x16x32_f16 v[38:41], v[74:77], v[98:101], v[38:41]
	v_mfma_f32_16x16x32_f16 v[30:33], v[66:69], v[176:179], v[30:33]
	v_mfma_f32_16x16x32_f16 v[22:25], v[74:77], v[176:179], v[22:25]
	v_mfma_f32_16x16x32_f16 v[14:17], v[66:69], v[184:187], v[14:17]
	v_mfma_f32_16x16x32_f16 v[10:13], v[74:77], v[184:187], v[10:13]
	v_mfma_f32_16x16x32_f16 v[62:65], v[70:73], v[94:97], v[62:65]
	v_mfma_f32_16x16x32_f16 v[58:61], v[78:81], v[94:97], v[58:61]
	v_mfma_f32_16x16x32_f16 v[46:49], v[70:73], v[102:105], v[46:49]
	v_mfma_f32_16x16x32_f16 v[38:41], v[78:81], v[102:105], v[38:41]
	v_mfma_f32_16x16x32_f16 v[30:33], v[70:73], v[180:183], v[30:33]
	v_mfma_f32_16x16x32_f16 v[22:25], v[78:81], v[180:183], v[22:25]
	v_mfma_f32_16x16x32_f16 v[14:17], v[70:73], v[188:191], v[14:17]
	v_mfma_f32_16x16x32_f16 v[10:13], v[78:81], v[188:191], v[10:13]
	v_mfma_f32_16x16x32_f16 v[54:57], v[196:199], v[90:93], v[54:57]
	v_mfma_f32_16x16x32_f16 v[50:53], v[204:207], v[90:93], v[50:53]
	v_mfma_f32_16x16x32_f16 v[42:45], v[196:199], v[98:101], v[42:45]
	v_mfma_f32_16x16x32_f16 v[34:37], v[204:207], v[98:101], v[34:37]
	v_mfma_f32_16x16x32_f16 v[26:29], v[196:199], v[176:179], v[26:29]
	v_mfma_f32_16x16x32_f16 v[18:21], v[204:207], v[176:179], v[18:21]
	v_mfma_f32_16x16x32_f16 v[6:9], v[196:199], v[184:187], v[6:9]
	v_mfma_f32_16x16x32_f16 v[2:5], v[204:207], v[184:187], v[2:5]
	v_mfma_f32_16x16x32_f16 v[54:57], v[200:203], v[94:97], v[54:57]
	v_mfma_f32_16x16x32_f16 v[50:53], v[220:223], v[94:97], v[50:53]
	v_mfma_f32_16x16x32_f16 v[42:45], v[200:203], v[102:105], v[42:45]
	v_mfma_f32_16x16x32_f16 v[34:37], v[220:223], v[102:105], v[34:37]
	v_mfma_f32_16x16x32_f16 v[26:29], v[200:203], v[180:183], v[26:29]
	v_mfma_f32_16x16x32_f16 v[18:21], v[220:223], v[180:183], v[18:21]
	v_mfma_f32_16x16x32_f16 v[6:9], v[200:203], v[188:191], v[6:9]
	v_mfma_f32_16x16x32_f16 v[2:5], v[220:223], v[188:191], v[2:5]
	s_barrier
	s_cbranch_scc1 .Lg4x_92

; #define PG8_STAGE(bufoff, gbase, voff) do { _Pragma("unroll") for (int _i = 0; _i < 2; ++_i) \
;         __builtin_amdgcn_global_load_lds((const unsigned*)((const char*)(gbase) + (voff)[_i]), (LAS unsigned*)(lds + (bufoff) + ldsw + _i * 8192), 16, 0, 0); } while (0)
; #define PG8_WAIT_V(n) asm volatile("s_waitcnt vmcnt(" #n ")" ::: "memory")
; #define PG8_BAR __builtin_amdgcn_s_barrier()
; template <class Epi, class AMap>
; __device__ __forceinline__ void gemm_phase(LAS unsigned char* lds, const AMap am, const int lda, const h16* Bt, const int ldb, const int M, const int N, const int K, const Epi& E) {
;     ...
;     for (int i = 0; i < 2; ++i) { int R, C; stage_rc(tid * 16 + i * 8192, R, C); const int Rb = Epi::PERM ? ((R & ~31) + perm32(R & 31)) : R;
;         voffA[i] = (unsigned)(R * lda + C) * 2u; voffB[i] = (unsigned)(Rb * ldb + C) * 2u; }
;     const size_t kstep = (size_t)(BK * 2);
;     const size_t hstepA = (size_t)HALF * lda * 2, hstepB = (size_t)HALF * ldb * 2;
;     const size_t tstepA = 2 * hstepA, tstepB = 2 * hstepB;
;     const unsigned ldsw = (unsigned)wid * 1024u;
;     const int aoff = lds_byte(wr * 64 + fr, fq * 8), boff = lds_byte(wc * 32 + fr, fq * 8);
;     ...
;     PG8_STAGE(PG8_SB(0, 0), cB, voffB); PG8_STAGE(PG8_SA(0, 0), cA, voffA); PG8_STAGE(PG8_SB(0, 1), cB + hstepB, voffB); PG8_STAGE(PG8_SA(0, 1), cA + hstepA, voffA);
;     if (wr == 1) PG8_BAR;
;     PG8_WAIT_V(4); PG8_BAR;
;     PG8_STAGE(PG8_SB(1, 0), cB + kstep, voffB); PG8_STAGE(PG8_SA(1, 0), cA + kstep, voffA); PG8_STAGE(PG8_SB(1, 1), cB + hstepB + kstep, voffB);
;     PG8_WAIT_V(6); PG8_BAR;
.LBB0_139:
	v_lshrrev_b32_e32 v18, 1, v8
	v_and_b32_e32 v18, 24, v18
	v_and_b32_e32 v9, 15, v8
	v_lshlrev_b32_e32 v19, 1, v18
	v_lshlrev_b32_e32 v8, 2, v8
	s_sext_i32_i8 s35, s0
	v_lshl_or_b32 v146, s20, 6, v9
	v_lshl_or_b32 v9, v9, 6, v19
	s_lshl_b32 s0, s20, 13
	v_and_b32_e32 v8, 32, v8
	v_bitop3_b32 v19, v9, s0, v8 bitop3:0xde
	s_lshl_b32 s0, s1, 5
	s_and_b32 s20, s0, 0x60
	v_lshl_add_u64 v[10:11], s[46:47], 0, v[0:1]
	v_mov_b32_e32 v135, v1
	s_lshl_b32 s0, s20, 7
	v_lshl_add_u64 v[12:13], s[46:47], 0, v[134:135]
	v_mov_b32_e32 v131, v1
	v_bitop3_b32 v147, v9, s0, v8 bitop3:0xde
	s_add_i32 m0, s23, 0x18000
	v_lshl_add_u64 v[8:9], v[10:11], 0, s[92:93]
	v_lshl_add_u64 v[14:15], s[26:27], 0, v[130:131]
	v_mov_b32_e32 v133, v1
	s_waitcnt vmcnt(0)
	s_barrier
	global_load_lds_dwordx4 v[8:9], off
	v_lshl_add_u64 v[8:9], v[12:13], 0, s[92:93]
	s_add_i32 m0, s23, 0x1a000
	s_add_i32 s74, s23, 0x8000
	s_add_i32 s75, s23, 0xa000
	v_lshl_add_u64 v[16:17], s[26:27], 0, v[132:133]
	global_load_lds_dwordx4 v[8:9], off
	v_lshl_add_u64 v[8:9], v[14:15], 0, s[92:93]
	s_mov_b32 m0, s74
	s_add_u32 s0, s46, 0x80080
	global_load_lds_dwordx4 v[8:9], off
	v_lshl_add_u64 v[8:9], v[16:17], 0, s[92:93]
	s_mov_b32 m0, s75
	s_addc_u32 s1, s47, 0
	global_load_lds_dwordx4 v[8:9], off
	s_add_i32 m0, s23, 0x1c000
	v_lshl_add_u64 v[8:9], s[0:1], 0, v[0:1]
	global_load_lds_dwordx4 v[8:9], off
	v_lshl_add_u64 v[8:9], s[0:1], 0, v[134:135]
	s_add_i32 m0, s23, 0x1e000
	v_or_b32_e32 v148, s20, v18
	global_load_lds_dwordx4 v[8:9], off
	v_lshlrev_b32_e32 v8, 15, v2
	v_and_b32_e32 v8, 0xffff0000, v8
	v_lshl_add_u32 v3, v3, 12, v8
	v_and_b32_e32 v2, 1, v2
	v_lshl_or_b32 v2, v2, 6, v3
	v_lshl_add_u32 v136, v4, 1, v2
	v_lshlrev_b32_e32 v2, 15, v5
	v_and_b32_e32 v2, 0xffff0000, v2
	s_waitcnt vmcnt(0)
	v_lshl_add_u32 v2, v6, 12, v2
	v_and_b32_e32 v3, 1, v5
	v_lshl_or_b32 v2, v3, 6, v2
	v_mov_b32_e32 v137, v1
	v_lshl_add_u32 v138, v7, 1, v2
	v_mov_b32_e32 v139, v1
	s_mov_b32 s76, 0
	v_add_u32_e32 v149, 0, v19
	s_barrier

; #define PG8_STAGE(bufoff, gbase, voff) do { _Pragma("unroll") for (int _i = 0; _i < 2; ++_i) \
;         __builtin_amdgcn_global_load_lds((const unsigned*)((const char*)(gbase) + (voff)[_i]), (LAS unsigned*)(lds + (bufoff) + ldsw + _i * 8192), 16, 0, 0); } while (0)
; #define PG8_LDA(dst, b, h) do { _Pragma("unroll") for (int m = 0; m < 4; ++m) _Pragma("unroll") for (int k = 0; k < 2; ++k) dst[m][k] = *(const LAS h16x8*)(lds + PG8_SA(b, h) + aoff + m * 2048 + k * 1024); } while (0)
; #define PG8_LDB(dst, b, h) do { _Pragma("unroll") for (int n = 0; n < 2; ++n) _Pragma("unroll") for (int k = 0; k < 2; ++k) dst[n][k] = *(const LAS h16x8*)(lds + PG8_SB(b, h) + boff + n * 2048 + k * 1024); } while (0)
; #define PG8_MMA(ai, bj, At, Bt_) do { __builtin_amdgcn_s_setprio(1); _Pragma("unroll") for (int m = 0; m < 4; ++m) _Pragma("unroll") for (int n = 0; n < 2; ++n) _Pragma("unroll") for (int k = 0; k < 2; ++k) \
;         acc[ai][bj][m][n] = __builtin_amdgcn_mfma_f32_16x16x32_f16(Bt_[n][k], At[m][k], acc[ai][bj][m][n], 0, 0, 0); __builtin_amdgcn_s_setprio(0); } while (0)
; #define PG8_WAIT_L(n) asm volatile("s_waitcnt lgkmcnt(" #n ")" ::: "memory")
; #define PG8_BAR __builtin_amdgcn_s_barrier()
; #define PG8_SCHED __builtin_amdgcn_sched_barrier(0)
; template <class Epi, class AMap>
; __device__ __forceinline__ void gemm_phase(LAS unsigned char* lds, const AMap am, const int lda, const h16* Bt, const int ldb, const int M, const int N, const int K, const Epi& E) {
;     ...
;             const bool last = (t == nt - 2);
;             const char* a1 = cA + (size_t)(t + 1) * kstep;
;             const char* a2 = last ? nA : cA + (size_t)(t + 2) * kstep; const char* b2 = last ? nB : cB + (size_t)(t + 2) * kstep;
;             const char* a3 = a2 + kstep; const char* b3 = b2 + kstep;
;             PG8_LDB(B0, 0, 0); PG8_SCHED; PG8_LDA(At, 0, 0); PG8_STAGE(PG8_SA(1, 1), a1 + hstepA, voffA);
;             PG8_WAIT_L(8); PG8_BAR; PG8_WAIT_L(0); PG8_MMA(0, 0, At, B0); PG8_BAR; PG8_SCHED;
;             PG8_LDB(B1, 0, 1); PG8_STAGE(PG8_SB(0, 0), b2, voffB);
;             PG8_BAR; PG8_WAIT_L(0); PG8_MMA(0, 1, At, B1); PG8_BAR;
;             PG8_LDA(At, 0, 1); PG8_STAGE(PG8_SA(0, 0), a2, voffA);
;             PG8_BAR; PG8_WAIT_L(0); PG8_MMA(1, 0, At, B0); PG8_BAR; PG8_SCHED;
;             PG8_STAGE(PG8_SB(0, 1), b2 + hstepB, voffB);
.Lg4p_147:
	s_add_u32 s46, s26, 0xfff80080
	s_addc_u32 s47, s27, -1
	s_add_i32 s60, 0, 0x10000
	v_add_u32_e32 v144, s60, v147
	ds_read_b128 v[140:143], v144
	ds_read_b128 v[150:153], v144 offset:1024
	ds_read_b128 v[154:157], v144 offset:2048
	ds_read_b128 v[158:161], v144 offset:3072
	s_cmp_eq_u32 s51, 28
	s_cselect_b32 s49, s41, s47
	s_cselect_b32 s48, s29, s46
	s_cselect_b32 s47, s1, s50
	s_cselect_b32 s46, s20, s21
	v_lshl_add_u64 v[144:145], s[26:27], 0, v[136:137]
	s_add_i32 m0, s23, 0xc000
	ds_read_b128 v[162:165], v149
	ds_read_b128 v[166:169], v149 offset:1024
	ds_read_b128 v[170:173], v149 offset:2048
	ds_read_b128 v[174:177], v149 offset:3072
	ds_read_b128 v[178:181], v149 offset:4096
	ds_read_b128 v[182:185], v149 offset:5120
	ds_read_b128 v[186:189], v149 offset:6144
	ds_read_b128 v[190:193], v149 offset:7168
	global_load_lds_dwordx4 v[144:145], off
	v_lshl_add_u64 v[144:145], s[26:27], 0, v[138:139]
	s_add_i32 m0, s23, 0xe000
	s_nop 0
	global_load_lds_dwordx4 v[144:145], off
	s_waitcnt lgkmcnt(11)
	s_add_i32 s66, 0, 0x14000
	v_add_u32_e32 v144, s66, v147
	s_add_i32 s60, s60, s64
	ds_read_b128 v[194:197], v144
	ds_read_b128 v[198:201], v144 offset:1024
	ds_read_b128 v[202:205], v144 offset:2048
	ds_read_b128 v[220:223], v144 offset:3072
	s_waitcnt vmcnt(40) lgkmcnt(0)
	s_barrier
	v_mfma_f32_16x16x32_f16 v[126:129], v[140:143], v[162:165], 0
	v_mfma_f32_16x16x32_f16 v[122:125], v[154:157], v[162:165], 0
	v_mfma_f32_16x16x32_f16 v[110:113], v[140:143], v[170:173], 0
	v_mfma_f32_16x16x32_f16 v[106:109], v[154:157], v[170:173], 0
	v_mfma_f32_16x16x32_f16 v[94:97], v[140:143], v[178:181], 0
	v_mfma_f32_16x16x32_f16 v[90:93], v[154:157], v[178:181], 0
	v_mfma_f32_16x16x32_f16 v[78:81], v[140:143], v[186:189], 0
	v_mfma_f32_16x16x32_f16 v[74:77], v[154:157], v[186:189], 0
	v_mfma_f32_16x16x32_f16 v[126:129], v[150:153], v[166:169], v[126:129]
	v_mfma_f32_16x16x32_f16 v[122:125], v[158:161], v[166:169], v[122:125]
	v_mfma_f32_16x16x32_f16 v[110:113], v[150:153], v[174:177], v[110:113]
	v_mfma_f32_16x16x32_f16 v[106:109], v[158:161], v[174:177], v[106:109]
	v_mfma_f32_16x16x32_f16 v[94:97], v[150:153], v[182:185], v[94:97]
	v_mfma_f32_16x16x32_f16 v[90:93], v[158:161], v[182:185], v[90:93]
	v_mfma_f32_16x16x32_f16 v[78:81], v[150:153], v[190:193], v[78:81]
	v_mfma_f32_16x16x32_f16 v[74:77], v[158:161], v[190:193], v[74:77]
	v_mfma_f32_16x16x32_f16 v[118:121], v[194:197], v[162:165], 0
	v_mfma_f32_16x16x32_f16 v[114:117], v[202:205], v[162:165], 0
	v_mfma_f32_16x16x32_f16 v[102:105], v[194:197], v[170:173], 0
	v_mfma_f32_16x16x32_f16 v[98:101], v[202:205], v[170:173], 0
	v_mfma_f32_16x16x32_f16 v[86:89], v[194:197], v[178:181], 0
	v_mfma_f32_16x16x32_f16 v[82:85], v[202:205], v[178:181], 0
	v_mfma_f32_16x16x32_f16 v[70:73], v[194:197], v[186:189], 0
	v_mfma_f32_16x16x32_f16 v[66:69], v[202:205], v[186:189], 0
	v_mfma_f32_16x16x32_f16 v[118:121], v[198:201], v[166:169], v[118:121]
	v_mfma_f32_16x16x32_f16 v[114:117], v[220:223], v[166:169], v[114:117]
	v_mfma_f32_16x16x32_f16 v[102:105], v[198:201], v[174:177], v[102:105]
	v_mfma_f32_16x16x32_f16 v[98:101], v[220:223], v[174:177], v[98:101]
	v_mfma_f32_16x16x32_f16 v[86:89], v[198:201], v[182:185], v[86:89]
	v_mfma_f32_16x16x32_f16 v[82:85], v[220:223], v[182:185], v[82:85]
	v_mfma_f32_16x16x32_f16 v[70:73], v[198:201], v[190:193], v[70:73]
	v_mfma_f32_16x16x32_f16 v[66:69], v[220:223], v[190:193], v[66:69]
	s_barrier
	v_lshl_add_u64 v[144:145], s[46:47], 0, v[0:1]
	s_mov_b32 m0, s60
	v_lshl_add_u64 v[206:207], s[46:47], 0, v[134:135]
	global_load_lds_dwordx4 v[144:145], off
	s_add_i32 m0, s60, 0x2000
	s_nop 0
	global_load_lds_dwordx4 v[206:207], off
	s_mov_b32 m0, s23
	v_lshl_add_u64 v[212:213], s[48:49], 0, v[130:131]
	ds_read_b128 v[162:165], v149 offset:16384
	ds_read_b128 v[166:169], v149 offset:17408
	ds_read_b128 v[170:173], v149 offset:18432
	ds_read_b128 v[174:177], v149 offset:19456
	ds_read_b128 v[178:181], v149 offset:20480
	ds_read_b128 v[182:185], v149 offset:21504
	ds_read_b128 v[186:189], v149 offset:22528
	ds_read_b128 v[190:193], v149 offset:23552
	global_load_lds_dwordx4 v[212:213], off
	v_lshl_add_u64 v[214:215], s[48:49], 0, v[132:133]
	s_mov_b32 m0, s71
	s_nop 0
	global_load_lds_dwordx4 v[214:215], off
	s_add_u32 s78, s46, 0x80000
	s_addc_u32 s79, s47, 0
	s_add_i32 s60, s66, s64
	v_lshl_add_u64 v[232:233], s[78:79], 0, v[0:1]
	s_mov_b32 m0, s60
	s_nop 0
	global_load_lds_dwordx4 v[232:233], off
	v_lshl_add_u64 v[232:233], s[78:79], 0, v[134:135]
	s_add_i32 m0, s60, 0x2000
	s_nop 0
	global_load_lds_dwordx4 v[232:233], off
	s_waitcnt vmcnt(40) lgkmcnt(0)
	s_barrier
; #define PG8_STAGE(bufoff, gbase, voff) do { _Pragma("unroll") for (int _i = 0; _i < 2; ++_i) \
;         __builtin_amdgcn_global_load_lds((const unsigned*)((const char*)(gbase) + (voff)[_i]), (LAS unsigned*)(lds + (bufoff) + ldsw + _i * 8192), 16, 0, 0); } while (0)
; #define PG8_LDA(dst, b, h) do { _Pragma("unroll") for (int m = 0; m < 4; ++m) _Pragma("unroll") for (int k = 0; k < 2; ++k) dst[m][k] = *(const LAS h16x8*)(lds + PG8_SA(b, h) + aoff + m * 2048 + k * 1024); } while (0)
; #define PG8_LDB(dst, b, h) do { _Pragma("unroll") for (int n = 0; n < 2; ++n) _Pragma("unroll") for (int k = 0; k < 2; ++k) dst[n][k] = *(const LAS h16x8*)(lds + PG8_SB(b, h) + boff + n * 2048 + k * 1024); } while (0)
; #define PG8_MMA(ai, bj, At, Bt_) do { __builtin_amdgcn_s_setprio(1); _Pragma("unroll") for (int m = 0; m < 4; ++m) _Pragma("unroll") for (int n = 0; n < 2; ++n) _Pragma("unroll") for (int k = 0; k < 2; ++k) \
;         acc[ai][bj][m][n] = __builtin_amdgcn_mfma_f32_16x16x32_f16(Bt_[n][k], At[m][k], acc[ai][bj][m][n], 0, 0, 0); __builtin_amdgcn_s_setprio(0); } while (0)
; #define PG8_WAIT_V(n) asm volatile("s_waitcnt vmcnt(" #n ")" ::: "memory")
; #define PG8_WAIT_L(n) asm volatile("s_waitcnt lgkmcnt(" #n ")" ::: "memory")
; #define PG8_BAR __builtin_amdgcn_s_barrier()
; #define PG8_SCHED __builtin_amdgcn_sched_barrier(0)
; template <class Epi, class AMap>
; __device__ __forceinline__ void gemm_phase(LAS unsigned char* lds, const AMap am, const int lda, const h16* Bt, const int ldb, const int M, const int N, const int K, const Epi& E) {
;     ...
;             PG8_WAIT_V(6); PG8_BAR; PG8_MMA(1, 1, At, B1); PG8_BAR;
;             PG8_LDB(B0, 1, 0); PG8_SCHED; PG8_LDA(At, 1, 0); PG8_STAGE(PG8_SA(0, 1), a2 + hstepA, voffA);
;             PG8_WAIT_L(8); PG8_BAR; PG8_WAIT_L(0); PG8_MMA(0, 0, At, B0); PG8_BAR; PG8_SCHED;
;             PG8_LDB(B1, 1, 1); PG8_STAGE(PG8_SB(1, 0), b3, voffB);
;             PG8_BAR; PG8_WAIT_L(0); PG8_MMA(0, 1, At, B1); PG8_BAR;
	v_mfma_f32_16x16x32_f16 v[62:65], v[140:143], v[162:165], 0
	v_mfma_f32_16x16x32_f16 v[58:61], v[154:157], v[162:165], 0
	v_mfma_f32_16x16x32_f16 v[46:49], v[140:143], v[170:173], 0
	v_mfma_f32_16x16x32_f16 v[42:45], v[154:157], v[170:173], 0
	v_mfma_f32_16x16x32_f16 v[30:33], v[140:143], v[178:181], 0
	v_mfma_f32_16x16x32_f16 v[26:29], v[154:157], v[178:181], 0
	v_mfma_f32_16x16x32_f16 v[14:17], v[140:143], v[186:189], 0
	v_mfma_f32_16x16x32_f16 v[10:13], v[154:157], v[186:189], 0
	v_mfma_f32_16x16x32_f16 v[62:65], v[150:153], v[166:169], v[62:65]
	v_mfma_f32_16x16x32_f16 v[58:61], v[158:161], v[166:169], v[58:61]
	v_mfma_f32_16x16x32_f16 v[46:49], v[150:153], v[174:177], v[46:49]
	v_mfma_f32_16x16x32_f16 v[42:45], v[158:161], v[174:177], v[42:45]
	v_mfma_f32_16x16x32_f16 v[30:33], v[150:153], v[182:185], v[30:33]
	v_mfma_f32_16x16x32_f16 v[26:29], v[158:161], v[182:185], v[26:29]
	v_mfma_f32_16x16x32_f16 v[14:17], v[150:153], v[190:193], v[14:17]
	v_mfma_f32_16x16x32_f16 v[10:13], v[158:161], v[190:193], v[10:13]
	v_mfma_f32_16x16x32_f16 v[54:57], v[194:197], v[162:165], 0
	v_mfma_f32_16x16x32_f16 v[50:53], v[202:205], v[162:165], 0
	v_mfma_f32_16x16x32_f16 v[38:41], v[194:197], v[170:173], 0
	v_mfma_f32_16x16x32_f16 v[34:37], v[202:205], v[170:173], 0
	v_mfma_f32_16x16x32_f16 v[22:25], v[194:197], v[178:181], 0
	v_mfma_f32_16x16x32_f16 v[18:21], v[202:205], v[178:181], 0
	v_mfma_f32_16x16x32_f16 v[6:9], v[194:197], v[186:189], 0
	v_mfma_f32_16x16x32_f16 v[2:5], v[202:205], v[186:189], 0
	v_mfma_f32_16x16x32_f16 v[54:57], v[198:201], v[166:169], v[54:57]
	v_mfma_f32_16x16x32_f16 v[50:53], v[220:223], v[166:169], v[50:53]
	v_mfma_f32_16x16x32_f16 v[38:41], v[198:201], v[174:177], v[38:41]
	v_mfma_f32_16x16x32_f16 v[34:37], v[220:223], v[174:177], v[34:37]
	v_mfma_f32_16x16x32_f16 v[22:25], v[198:201], v[182:185], v[22:25]
	v_mfma_f32_16x16x32_f16 v[18:21], v[220:223], v[182:185], v[18:21]
	v_mfma_f32_16x16x32_f16 v[6:9], v[198:201], v[190:193], v[6:9]
	v_mfma_f32_16x16x32_f16 v[2:5], v[220:223], v[190:193], v[2:5]
	s_barrier
	s_add_i32 s60, 0, 0x18000
	v_add_u32_e32 v234, s60, v147
	ds_read_b128 v[140:143], v234
	ds_read_b128 v[150:153], v234 offset:1024
	ds_read_b128 v[154:157], v234 offset:2048
	ds_read_b128 v[158:161], v234 offset:3072
	s_add_u32 s48, s48, 0x80000
	s_addc_u32 s49, s49, 0
	s_mov_b32 m0, s72
	v_lshl_add_u64 v[232:233], s[48:49], 0, v[130:131]
	ds_read_b128 v[162:165], v149 offset:32768
	ds_read_b128 v[166:169], v149 offset:33792
	ds_read_b128 v[170:173], v149 offset:34816
	ds_read_b128 v[174:177], v149 offset:35840
	ds_read_b128 v[178:181], v149 offset:36864
	ds_read_b128 v[182:185], v149 offset:37888
	ds_read_b128 v[186:189], v149 offset:38912
	ds_read_b128 v[190:193], v149 offset:39936
	global_load_lds_dwordx4 v[232:233], off
	v_lshl_add_u64 v[232:233], s[48:49], 0, v[132:133]
	s_mov_b32 m0, s73
	s_nop 0
	global_load_lds_dwordx4 v[232:233], off
	s_waitcnt lgkmcnt(11)
	s_add_i32 s48, 0, 0x1c000
	s_add_i32 s49, s60, s64
	v_add_u32_e32 v216, s48, v147
	v_lshl_add_u64 v[144:145], v[144:145], 0, s[92:93]
	s_mov_b32 m0, s49
	ds_read_b128 v[194:197], v216
	ds_read_b128 v[198:201], v216 offset:1024
	ds_read_b128 v[202:205], v216 offset:2048
	ds_read_b128 v[220:223], v216 offset:3072
	s_waitcnt vmcnt(8) lgkmcnt(0)
	s_barrier
	v_mfma_f32_16x16x32_f16 v[126:129], v[140:143], v[162:165], v[126:129]
	v_mfma_f32_16x16x32_f16 v[122:125], v[154:157], v[162:165], v[122:125]
	v_mfma_f32_16x16x32_f16 v[110:113], v[140:143], v[170:173], v[110:113]
	v_mfma_f32_16x16x32_f16 v[106:109], v[154:157], v[170:173], v[106:109]
	v_mfma_f32_16x16x32_f16 v[94:97], v[140:143], v[178:181], v[94:97]
	v_mfma_f32_16x16x32_f16 v[90:93], v[154:157], v[178:181], v[90:93]
	v_mfma_f32_16x16x32_f16 v[78:81], v[140:143], v[186:189], v[78:81]
	v_mfma_f32_16x16x32_f16 v[74:77], v[154:157], v[186:189], v[74:77]
	v_mfma_f32_16x16x32_f16 v[126:129], v[150:153], v[166:169], v[126:129]
	v_mfma_f32_16x16x32_f16 v[122:125], v[158:161], v[166:169], v[122:125]
	v_mfma_f32_16x16x32_f16 v[110:113], v[150:153], v[174:177], v[110:113]
	v_mfma_f32_16x16x32_f16 v[106:109], v[158:161], v[174:177], v[106:109]
	v_mfma_f32_16x16x32_f16 v[94:97], v[150:153], v[182:185], v[94:97]
	v_mfma_f32_16x16x32_f16 v[90:93], v[158:161], v[182:185], v[90:93]
	v_mfma_f32_16x16x32_f16 v[78:81], v[150:153], v[190:193], v[78:81]
	v_mfma_f32_16x16x32_f16 v[74:77], v[158:161], v[190:193], v[74:77]
	v_mfma_f32_16x16x32_f16 v[118:121], v[194:197], v[162:165], v[118:121]
	v_mfma_f32_16x16x32_f16 v[114:117], v[202:205], v[162:165], v[114:117]
	v_mfma_f32_16x16x32_f16 v[102:105], v[194:197], v[170:173], v[102:105]
	v_mfma_f32_16x16x32_f16 v[98:101], v[202:205], v[170:173], v[98:101]
	v_mfma_f32_16x16x32_f16 v[86:89], v[194:197], v[178:181], v[86:89]
	v_mfma_f32_16x16x32_f16 v[82:85], v[202:205], v[178:181], v[82:85]
	v_mfma_f32_16x16x32_f16 v[70:73], v[194:197], v[186:189], v[70:73]
	v_mfma_f32_16x16x32_f16 v[66:69], v[202:205], v[186:189], v[66:69]
	v_mfma_f32_16x16x32_f16 v[118:121], v[198:201], v[166:169], v[118:121]
	v_mfma_f32_16x16x32_f16 v[114:117], v[220:223], v[166:169], v[114:117]
	v_mfma_f32_16x16x32_f16 v[102:105], v[198:201], v[174:177], v[102:105]
	v_mfma_f32_16x16x32_f16 v[98:101], v[220:223], v[174:177], v[98:101]
	v_mfma_f32_16x16x32_f16 v[86:89], v[198:201], v[182:185], v[86:89]
	v_mfma_f32_16x16x32_f16 v[82:85], v[220:223], v[182:185], v[82:85]
	v_mfma_f32_16x16x32_f16 v[70:73], v[198:201], v[190:193], v[70:73]
	v_mfma_f32_16x16x32_f16 v[66:69], v[220:223], v[190:193], v[66:69]
	s_barrier
; #define PG8_STAGE(bufoff, gbase, voff) do { _Pragma("unroll") for (int _i = 0; _i < 2; ++_i) \
;         __builtin_amdgcn_global_load_lds((const unsigned*)((const char*)(gbase) + (voff)[_i]), (LAS unsigned*)(lds + (bufoff) + ldsw + _i * 8192), 16, 0, 0); } while (0)
; #define PG8_LDA(dst, b, h) do { _Pragma("unroll") for (int m = 0; m < 4; ++m) _Pragma("unroll") for (int k = 0; k < 2; ++k) dst[m][k] = *(const LAS h16x8*)(lds + PG8_SA(b, h) + aoff + m * 2048 + k * 1024); } while (0)
; #define PG8_MMA(ai, bj, At, Bt_) do { __builtin_amdgcn_s_setprio(1); _Pragma("unroll") for (int m = 0; m < 4; ++m) _Pragma("unroll") for (int n = 0; n < 2; ++n) _Pragma("unroll") for (int k = 0; k < 2; ++k) \
;         acc[ai][bj][m][n] = __builtin_amdgcn_mfma_f32_16x16x32_f16(Bt_[n][k], At[m][k], acc[ai][bj][m][n], 0, 0, 0); __builtin_amdgcn_s_setprio(0); } while (0)
; #define PG8_WAIT_V(n) asm volatile("s_waitcnt vmcnt(" #n ")" ::: "memory")
; #define PG8_WAIT_L(n) asm volatile("s_waitcnt lgkmcnt(" #n ")" ::: "memory")
; #define PG8_BAR __builtin_amdgcn_s_barrier()
; #define PG8_SCHED __builtin_amdgcn_sched_barrier(0)
; template <class Epi, class AMap>
; __device__ __forceinline__ void gemm_phase(LAS unsigned char* lds, const AMap am, const int lda, const h16* Bt, const int ldb, const int M, const int N, const int K, const Epi& E) {
;     ...
;             PG8_LDA(At, 1, 1); PG8_STAGE(PG8_SA(1, 0), a3, voffA);
;             PG8_BAR; PG8_WAIT_L(0); PG8_MMA(1, 0, At, B0); PG8_BAR; PG8_SCHED;
;             PG8_STAGE(PG8_SB(1, 1), b3 + hstepB, voffB);
;             PG8_WAIT_V(6); PG8_BAR; PG8_MMA(1, 1, At, B1); PG8_BAR;
;         }
	global_load_lds_dwordx4 v[144:145], off
	v_lshl_add_u64 v[144:145], v[206:207], 0, s[92:93]
	s_add_i32 m0, s49, 0x2000
	s_nop 0
	global_load_lds_dwordx4 v[144:145], off
	s_mov_b32 m0, s74
	v_lshl_add_u64 v[144:145], v[212:213], 0, s[92:93]
	ds_read_b128 v[162:165], v149 offset:49152
	ds_read_b128 v[166:169], v149 offset:50176
	ds_read_b128 v[170:173], v149 offset:51200
	ds_read_b128 v[174:177], v149 offset:52224
	ds_read_b128 v[178:181], v149 offset:53248
	ds_read_b128 v[182:185], v149 offset:54272
	ds_read_b128 v[186:189], v149 offset:55296
	ds_read_b128 v[190:193], v149 offset:56320
	global_load_lds_dwordx4 v[144:145], off
	v_lshl_add_u64 v[144:145], v[214:215], 0, s[92:93]
	s_mov_b32 m0, s75
	s_nop 0
	global_load_lds_dwordx4 v[144:145], off
	s_add_u32 s46, s46, 0x80080
	s_addc_u32 s47, s47, 0
	s_add_i32 s48, s48, s64
	v_lshl_add_u64 v[232:233], s[46:47], 0, v[0:1]
	s_mov_b32 m0, s48
	s_nop 0
	global_load_lds_dwordx4 v[232:233], off
	v_lshl_add_u64 v[232:233], s[46:47], 0, v[134:135]
	s_add_i32 m0, s48, 0x2000
	s_nop 0
	global_load_lds_dwordx4 v[232:233], off
	s_add_i32 s51, s51, 2
	s_add_u32 s26, s26, 0x100
	s_addc_u32 s27, s27, 0
	s_add_u32 s21, s21, 0x100
	s_addc_u32 s50, s50, 0
	s_cmp_gt_u32 s51, 29
	s_waitcnt vmcnt(8) lgkmcnt(0)
	s_barrier
	v_mfma_f32_16x16x32_f16 v[62:65], v[140:143], v[162:165], v[62:65]
	v_mfma_f32_16x16x32_f16 v[58:61], v[154:157], v[162:165], v[58:61]
	v_mfma_f32_16x16x32_f16 v[46:49], v[140:143], v[170:173], v[46:49]
	v_mfma_f32_16x16x32_f16 v[42:45], v[154:157], v[170:173], v[42:45]
	v_mfma_f32_16x16x32_f16 v[30:33], v[140:143], v[178:181], v[30:33]
	v_mfma_f32_16x16x32_f16 v[26:29], v[154:157], v[178:181], v[26:29]
	v_mfma_f32_16x16x32_f16 v[14:17], v[140:143], v[186:189], v[14:17]
	v_mfma_f32_16x16x32_f16 v[10:13], v[154:157], v[186:189], v[10:13]
	v_mfma_f32_16x16x32_f16 v[62:65], v[150:153], v[166:169], v[62:65]
	v_mfma_f32_16x16x32_f16 v[58:61], v[158:161], v[166:169], v[58:61]
	v_mfma_f32_16x16x32_f16 v[46:49], v[150:153], v[174:177], v[46:49]
	v_mfma_f32_16x16x32_f16 v[42:45], v[158:161], v[174:177], v[42:45]
	v_mfma_f32_16x16x32_f16 v[30:33], v[150:153], v[182:185], v[30:33]
	v_mfma_f32_16x16x32_f16 v[26:29], v[158:161], v[182:185], v[26:29]
	v_mfma_f32_16x16x32_f16 v[14:17], v[150:153], v[190:193], v[14:17]
	v_mfma_f32_16x16x32_f16 v[10:13], v[158:161], v[190:193], v[10:13]
	v_mfma_f32_16x16x32_f16 v[54:57], v[194:197], v[162:165], v[54:57]
	v_mfma_f32_16x16x32_f16 v[50:53], v[202:205], v[162:165], v[50:53]
	v_mfma_f32_16x16x32_f16 v[38:41], v[194:197], v[170:173], v[38:41]
	v_mfma_f32_16x16x32_f16 v[34:37], v[202:205], v[170:173], v[34:37]
	v_mfma_f32_16x16x32_f16 v[22:25], v[194:197], v[178:181], v[22:25]
	v_mfma_f32_16x16x32_f16 v[18:21], v[202:205], v[178:181], v[18:21]
	v_mfma_f32_16x16x32_f16 v[6:9], v[194:197], v[186:189], v[6:9]
	v_mfma_f32_16x16x32_f16 v[2:5], v[202:205], v[186:189], v[2:5]
	v_mfma_f32_16x16x32_f16 v[54:57], v[198:201], v[166:169], v[54:57]
	v_mfma_f32_16x16x32_f16 v[50:53], v[220:223], v[166:169], v[50:53]
	v_mfma_f32_16x16x32_f16 v[38:41], v[198:201], v[174:177], v[38:41]
	v_mfma_f32_16x16x32_f16 v[34:37], v[220:223], v[174:177], v[34:37]
	v_mfma_f32_16x16x32_f16 v[22:25], v[198:201], v[182:185], v[22:25]
	v_mfma_f32_16x16x32_f16 v[18:21], v[220:223], v[182:185], v[18:21]
	v_mfma_f32_16x16x32_f16 v[6:9], v[198:201], v[190:193], v[6:9]
	v_mfma_f32_16x16x32_f16 v[2:5], v[220:223], v[190:193], v[2:5]
	s_barrier
	s_cbranch_scc1 .Lg4x_147

; #define PG8_STAGE(bufoff, gbase, voff) do { _Pragma("unroll") for (int _i = 0; _i < 2; ++_i) \
;         __builtin_amdgcn_global_load_lds((const unsigned*)((const char*)(gbase) + (voff)[_i]), (LAS unsigned*)(lds + (bufoff) + ldsw + _i * 8192), 16, 0, 0); } while (0)
; #define PG8_WAIT_V(n) asm volatile("s_waitcnt vmcnt(" #n ")" ::: "memory")
; #define PG8_BAR __builtin_amdgcn_s_barrier()
; template <class Epi, class AMap>
; __device__ __forceinline__ void gemm_phase(LAS unsigned char* lds, const AMap am, const int lda, const h16* Bt, const int ldb, const int M, const int N, const int K, const Epi& E) {
;     ...
;     PG8_STAGE(PG8_SB(0, 0), cB, voffB); PG8_STAGE(PG8_SA(0, 0), cA, voffA); PG8_STAGE(PG8_SB(0, 1), cB + hstepB, voffB); PG8_STAGE(PG8_SA(0, 1), cA + hstepA, voffA);
;     if (wr == 1) PG8_BAR;
;     PG8_WAIT_V(4); PG8_BAR;
;     PG8_STAGE(PG8_SB(1, 0), cB + kstep, voffB); PG8_STAGE(PG8_SA(1, 0), cA + kstep, voffA); PG8_STAGE(PG8_SB(1, 1), cB + hstepB + kstep, voffB);
;     PG8_WAIT_V(6); PG8_BAR;
.LBB0_780:
	v_lshrrev_b32_e32 v18, 1, v2
	v_and_b32_e32 v18, 24, v18
	v_and_b32_e32 v9, 15, v2
	v_lshlrev_b32_e32 v19, 1, v18
	v_lshlrev_b32_e32 v2, 2, v2
	v_lshl_or_b32 v154, s20, 6, v9
	v_lshl_or_b32 v9, v9, 6, v19
	s_lshl_b32 s0, s20, 13
	v_and_b32_e32 v2, 32, v2
	v_lshl_add_u64 v[10:11], s[40:41], 0, v[0:1]
	v_mov_b32_e32 v143, v1
	v_bitop3_b32 v19, v9, s0, v2 bitop3:0xde
	s_lshl_b32 s0, s21, 5
	v_lshl_add_u64 v[12:13], s[40:41], 0, v[142:143]
	v_mov_b32_e32 v139, v1
	s_and_b32 s20, s0, 0x60
	s_add_i32 m0, s23, 0x18000
	v_lshl_add_u64 v[10:11], v[10:11], 0, s[92:93]
	v_lshl_add_u64 v[14:15], s[48:49], 0, v[138:139]
	v_mov_b32_e32 v141, v1
	s_lshl_b32 s0, s20, 7
	s_waitcnt vmcnt(0)
	s_barrier
	global_load_lds_dwordx4 v[10:11], off
	v_lshl_add_u64 v[10:11], v[12:13], 0, s[92:93]
	s_add_i32 m0, s23, 0x1a000
	s_add_i32 s75, s23, 0x8000
	s_add_i32 s76, s23, 0xa000
	v_lshl_add_u64 v[16:17], s[48:49], 0, v[140:141]
	v_bitop3_b32 v155, v9, s0, v2 bitop3:0xde
	global_load_lds_dwordx4 v[10:11], off
	v_lshl_add_u64 v[10:11], v[14:15], 0, s[92:93]
	s_mov_b32 m0, s75
	s_add_u32 s0, s40, 0x80080
	global_load_lds_dwordx4 v[10:11], off
	v_lshl_add_u64 v[10:11], v[16:17], 0, s[92:93]
	s_mov_b32 m0, s76
	s_addc_u32 s1, s41, 0
	global_load_lds_dwordx4 v[10:11], off
	s_add_i32 m0, s23, 0x1c000
	v_lshl_add_u64 v[10:11], s[0:1], 0, v[0:1]
	global_load_lds_dwordx4 v[10:11], off
	v_lshl_add_u64 v[10:11], s[0:1], 0, v[142:143]
	s_add_i32 m0, s23, 0x1e000
	v_cvt_f32_ubyte0_e32 v2, s68
	global_load_lds_dwordx4 v[10:11], off
	v_rcp_iflag_f32_e32 v2, v2
	s_sub_i32 s0, 0, s68
	s_waitcnt vmcnt(0)
	v_or_b32_e32 v156, s20, v18
	v_mul_f32_e32 v2, 0x4f7ffffe, v2
	v_cvt_u32_f32_e32 v2, v2
	s_mov_b32 s77, 0
	v_mov_b32_e32 v145, v1
	v_mov_b32_e32 v147, v1
	v_readfirstlane_b32 s1, v2
	v_lshlrev_b32_e32 v2, 15, v3
	v_and_b32_e32 v2, 0xffff0000, v2
	v_lshl_add_u32 v2, v4, 12, v2
	v_and_b32_e32 v3, 1, v3
	v_lshl_or_b32 v2, v3, 6, v2
	v_lshl_add_u32 v144, v5, 1, v2
	v_lshlrev_b32_e32 v2, 15, v6
	v_and_b32_e32 v2, 0xffff0000, v2
	s_mul_i32 s0, s0, s1
	v_lshl_add_u32 v2, v7, 12, v2
	v_and_b32_e32 v3, 1, v6
	s_mul_hi_u32 s0, s1, s0
	v_lshl_or_b32 v2, v3, 6, v2
	s_add_i32 s78, s1, s0
	v_lshl_add_u32 v146, v8, 1, v2
	v_add_u32_e32 v157, 0, v19
	s_barrier
	s_branch .LBB0_782

; #define PG8_STAGE(bufoff, gbase, voff) do { _Pragma("unroll") for (int _i = 0; _i < 2; ++_i) \
;         __builtin_amdgcn_global_load_lds((const unsigned*)((const char*)(gbase) + (voff)[_i]), (LAS unsigned*)(lds + (bufoff) + ldsw + _i * 8192), 16, 0, 0); } while (0)
; #define PG8_LDA(dst, b, h) do { _Pragma("unroll") for (int m = 0; m < 4; ++m) _Pragma("unroll") for (int k = 0; k < 2; ++k) dst[m][k] = *(const LAS h16x8*)(lds + PG8_SA(b, h) + aoff + m * 2048 + k * 1024); } while (0)
; #define PG8_LDB(dst, b, h) do { _Pragma("unroll") for (int n = 0; n < 2; ++n) _Pragma("unroll") for (int k = 0; k < 2; ++k) dst[n][k] = *(const LAS h16x8*)(lds + PG8_SB(b, h) + boff + n * 2048 + k * 1024); } while (0)
; #define PG8_MMA(ai, bj, At, Bt_) do { __builtin_amdgcn_s_setprio(1); _Pragma("unroll") for (int m = 0; m < 4; ++m) _Pragma("unroll") for (int n = 0; n < 2; ++n) _Pragma("unroll") for (int k = 0; k < 2; ++k) \
;         acc[ai][bj][m][n] = __builtin_amdgcn_mfma_f32_16x16x32_f16(Bt_[n][k], At[m][k], acc[ai][bj][m][n], 0, 0, 0); __builtin_amdgcn_s_setprio(0); } while (0)
; #define PG8_WAIT_L(n) asm volatile("s_waitcnt lgkmcnt(" #n ")" ::: "memory")
; #define PG8_BAR __builtin_amdgcn_s_barrier()
; #define PG8_SCHED __builtin_amdgcn_sched_barrier(0)
; template <class Epi, class AMap>
; __device__ __forceinline__ void gemm_phase(LAS unsigned char* lds, const AMap am, const int lda, const h16* Bt, const int ldb, const int M, const int N, const int K, const Epi& E) {
;     ...
;             const bool last = (t == nt - 2);
;             const char* a1 = cA + (size_t)(t + 1) * kstep;
;             const char* a2 = last ? nA : cA + (size_t)(t + 2) * kstep; const char* b2 = last ? nB : cB + (size_t)(t + 2) * kstep;
;             const char* a3 = a2 + kstep; const char* b3 = b2 + kstep;
;             PG8_LDB(B0, 0, 0); PG8_SCHED; PG8_LDA(At, 0, 0); PG8_STAGE(PG8_SA(1, 1), a1 + hstepA, voffA);
;             PG8_WAIT_L(8); PG8_BAR; PG8_WAIT_L(0); PG8_MMA(0, 0, At, B0); PG8_BAR; PG8_SCHED;
;             PG8_LDB(B1, 0, 1); PG8_STAGE(PG8_SB(0, 0), b2, voffB);
;             PG8_BAR; PG8_WAIT_L(0); PG8_MMA(0, 1, At, B1); PG8_BAR;
;             PG8_LDA(At, 0, 1); PG8_STAGE(PG8_SA(0, 0), a2, voffA);
;             PG8_BAR; PG8_WAIT_L(0); PG8_MMA(1, 0, At, B0); PG8_BAR; PG8_SCHED;
;             PG8_STAGE(PG8_SB(0, 1), b2 + hstepB, voffB);
.Lg4p_799:
	s_add_u32 s40, s0, 0xfff80080
	s_addc_u32 s41, s1, -1
	s_add_i32 s45, 0, 0x10000
	v_add_u32_e32 v152, s45, v155
	ds_read_b128 v[130:133], v152
	ds_read_b128 v[134:137], v152 offset:1024
	ds_read_b128 v[148:151], v152 offset:2048
	ds_read_b128 v[158:161], v152 offset:3072
	s_cmp_eq_u32 s43, 28
	s_cselect_b32 s49, s47, s41
	s_cselect_b32 s48, s46, s40
	s_cselect_b32 s41, s29, s35
	s_cselect_b32 s40, s20, s21
	v_lshl_add_u64 v[152:153], s[0:1], 0, v[144:145]
	s_add_i32 m0, s23, 0xc000
	ds_read_b128 v[162:165], v157
	ds_read_b128 v[166:169], v157 offset:1024
	ds_read_b128 v[170:173], v157 offset:2048
	ds_read_b128 v[174:177], v157 offset:3072
	ds_read_b128 v[178:181], v157 offset:4096
	ds_read_b128 v[182:185], v157 offset:5120
	ds_read_b128 v[186:189], v157 offset:6144
	ds_read_b128 v[190:193], v157 offset:7168
	global_load_lds_dwordx4 v[152:153], off
	v_lshl_add_u64 v[152:153], s[0:1], 0, v[146:147]
	s_add_i32 m0, s23, 0xe000
	s_nop 0
	global_load_lds_dwordx4 v[152:153], off
	s_waitcnt lgkmcnt(11)
	s_add_i32 s60, 0, 0x14000
	v_add_u32_e32 v152, s60, v155
	s_add_i32 s45, s45, s72
	ds_read_b128 v[194:197], v152
	ds_read_b128 v[198:201], v152 offset:1024
	ds_read_b128 v[202:205], v152 offset:2048
	ds_read_b128 v[220:223], v152 offset:3072
	s_waitcnt vmcnt(24) lgkmcnt(0)
	s_barrier
	v_mfma_f32_16x16x32_f16 v[126:129], v[130:133], v[162:165], 0
	v_mfma_f32_16x16x32_f16 v[122:125], v[148:151], v[162:165], 0
	v_mfma_f32_16x16x32_f16 v[110:113], v[130:133], v[170:173], 0
	v_mfma_f32_16x16x32_f16 v[106:109], v[148:151], v[170:173], 0
	v_mfma_f32_16x16x32_f16 v[94:97], v[130:133], v[178:181], 0
	v_mfma_f32_16x16x32_f16 v[90:93], v[148:151], v[178:181], 0
	v_mfma_f32_16x16x32_f16 v[78:81], v[130:133], v[186:189], 0
	v_mfma_f32_16x16x32_f16 v[74:77], v[148:151], v[186:189], 0
	v_mfma_f32_16x16x32_f16 v[126:129], v[134:137], v[166:169], v[126:129]
	v_mfma_f32_16x16x32_f16 v[122:125], v[158:161], v[166:169], v[122:125]
	v_mfma_f32_16x16x32_f16 v[110:113], v[134:137], v[174:177], v[110:113]
	v_mfma_f32_16x16x32_f16 v[106:109], v[158:161], v[174:177], v[106:109]
	v_mfma_f32_16x16x32_f16 v[94:97], v[134:137], v[182:185], v[94:97]
	v_mfma_f32_16x16x32_f16 v[90:93], v[158:161], v[182:185], v[90:93]
	v_mfma_f32_16x16x32_f16 v[78:81], v[134:137], v[190:193], v[78:81]
	v_mfma_f32_16x16x32_f16 v[74:77], v[158:161], v[190:193], v[74:77]
	v_mfma_f32_16x16x32_f16 v[118:121], v[194:197], v[162:165], 0
	v_mfma_f32_16x16x32_f16 v[114:117], v[202:205], v[162:165], 0
	v_mfma_f32_16x16x32_f16 v[102:105], v[194:197], v[170:173], 0
	v_mfma_f32_16x16x32_f16 v[98:101], v[202:205], v[170:173], 0
	v_mfma_f32_16x16x32_f16 v[86:89], v[194:197], v[178:181], 0
	v_mfma_f32_16x16x32_f16 v[82:85], v[202:205], v[178:181], 0
	v_mfma_f32_16x16x32_f16 v[70:73], v[194:197], v[186:189], 0
	v_mfma_f32_16x16x32_f16 v[66:69], v[202:205], v[186:189], 0
	v_mfma_f32_16x16x32_f16 v[118:121], v[198:201], v[166:169], v[118:121]
	v_mfma_f32_16x16x32_f16 v[114:117], v[220:223], v[166:169], v[114:117]
	v_mfma_f32_16x16x32_f16 v[102:105], v[198:201], v[174:177], v[102:105]
	v_mfma_f32_16x16x32_f16 v[98:101], v[220:223], v[174:177], v[98:101]
	v_mfma_f32_16x16x32_f16 v[86:89], v[198:201], v[182:185], v[86:89]
	v_mfma_f32_16x16x32_f16 v[82:85], v[220:223], v[182:185], v[82:85]
	v_mfma_f32_16x16x32_f16 v[70:73], v[198:201], v[190:193], v[70:73]
	v_mfma_f32_16x16x32_f16 v[66:69], v[220:223], v[190:193], v[66:69]
	s_barrier
	v_lshl_add_u64 v[152:153], s[40:41], 0, v[0:1]
	s_mov_b32 m0, s45
	v_lshl_add_u64 v[206:207], s[40:41], 0, v[142:143]
	global_load_lds_dwordx4 v[152:153], off
	s_add_i32 m0, s45, 0x2000
	s_nop 0
	global_load_lds_dwordx4 v[206:207], off
	s_mov_b32 m0, s23
	v_lshl_add_u64 v[212:213], s[48:49], 0, v[138:139]
	ds_read_b128 v[162:165], v157 offset:16384
	ds_read_b128 v[166:169], v157 offset:17408
	ds_read_b128 v[170:173], v157 offset:18432
	ds_read_b128 v[174:177], v157 offset:19456
	ds_read_b128 v[178:181], v157 offset:20480
	ds_read_b128 v[182:185], v157 offset:21504
	ds_read_b128 v[186:189], v157 offset:22528
	ds_read_b128 v[190:193], v157 offset:23552
	global_load_lds_dwordx4 v[212:213], off
	v_lshl_add_u64 v[224:225], s[48:49], 0, v[140:141]
	s_mov_b32 m0, s27
	s_nop 0
	global_load_lds_dwordx4 v[224:225], off
	s_add_u32 s50, s40, 0x80000
	s_addc_u32 s51, s41, 0
	s_add_i32 s45, s60, s72
	v_lshl_add_u64 v[232:233], s[50:51], 0, v[0:1]
	s_mov_b32 m0, s45
	s_nop 0
	global_load_lds_dwordx4 v[232:233], off
	v_lshl_add_u64 v[232:233], s[50:51], 0, v[142:143]
	s_add_i32 m0, s45, 0x2000
	s_nop 0
	global_load_lds_dwordx4 v[232:233], off
	s_waitcnt vmcnt(24) lgkmcnt(0)
	s_barrier
; #define PG8_STAGE(bufoff, gbase, voff) do { _Pragma("unroll") for (int _i = 0; _i < 2; ++_i) \
;         __builtin_amdgcn_global_load_lds((const unsigned*)((const char*)(gbase) + (voff)[_i]), (LAS unsigned*)(lds + (bufoff) + ldsw + _i * 8192), 16, 0, 0); } while (0)
; #define PG8_LDA(dst, b, h) do { _Pragma("unroll") for (int m = 0; m < 4; ++m) _Pragma("unroll") for (int k = 0; k < 2; ++k) dst[m][k] = *(const LAS h16x8*)(lds + PG8_SA(b, h) + aoff + m * 2048 + k * 1024); } while (0)
; #define PG8_LDB(dst, b, h) do { _Pragma("unroll") for (int n = 0; n < 2; ++n) _Pragma("unroll") for (int k = 0; k < 2; ++k) dst[n][k] = *(const LAS h16x8*)(lds + PG8_SB(b, h) + boff + n * 2048 + k * 1024); } while (0)
; #define PG8_MMA(ai, bj, At, Bt_) do { __builtin_amdgcn_s_setprio(1); _Pragma("unroll") for (int m = 0; m < 4; ++m) _Pragma("unroll") for (int n = 0; n < 2; ++n) _Pragma("unroll") for (int k = 0; k < 2; ++k) \
;         acc[ai][bj][m][n] = __builtin_amdgcn_mfma_f32_16x16x32_f16(Bt_[n][k], At[m][k], acc[ai][bj][m][n], 0, 0, 0); __builtin_amdgcn_s_setprio(0); } while (0)
; #define PG8_WAIT_V(n) asm volatile("s_waitcnt vmcnt(" #n ")" ::: "memory")
; #define PG8_WAIT_L(n) asm volatile("s_waitcnt lgkmcnt(" #n ")" ::: "memory")
; #define PG8_BAR __builtin_amdgcn_s_barrier()
; #define PG8_SCHED __builtin_amdgcn_sched_barrier(0)
; template <class Epi, class AMap>
; __device__ __forceinline__ void gemm_phase(LAS unsigned char* lds, const AMap am, const int lda, const h16* Bt, const int ldb, const int M, const int N, const int K, const Epi& E) {
;     ...
;             PG8_WAIT_V(6); PG8_BAR; PG8_MMA(1, 1, At, B1); PG8_BAR;
;             PG8_LDB(B0, 1, 0); PG8_SCHED; PG8_LDA(At, 1, 0); PG8_STAGE(PG8_SA(0, 1), a2 + hstepA, voffA);
;             PG8_WAIT_L(8); PG8_BAR; PG8_WAIT_L(0); PG8_MMA(0, 0, At, B0); PG8_BAR; PG8_SCHED;
;             PG8_LDB(B1, 1, 1); PG8_STAGE(PG8_SB(1, 0), b3, voffB);
;             PG8_BAR; PG8_WAIT_L(0); PG8_MMA(0, 1, At, B1); PG8_BAR;
	v_mfma_f32_16x16x32_f16 v[62:65], v[130:133], v[162:165], 0
	v_mfma_f32_16x16x32_f16 v[58:61], v[148:151], v[162:165], 0
	v_mfma_f32_16x16x32_f16 v[46:49], v[130:133], v[170:173], 0
	v_mfma_f32_16x16x32_f16 v[42:45], v[148:151], v[170:173], 0
	v_mfma_f32_16x16x32_f16 v[30:33], v[130:133], v[178:181], 0
	v_mfma_f32_16x16x32_f16 v[26:29], v[148:151], v[178:181], 0
	v_mfma_f32_16x16x32_f16 v[14:17], v[130:133], v[186:189], 0
	v_mfma_f32_16x16x32_f16 v[10:13], v[148:151], v[186:189], 0
	v_mfma_f32_16x16x32_f16 v[62:65], v[134:137], v[166:169], v[62:65]
	v_mfma_f32_16x16x32_f16 v[58:61], v[158:161], v[166:169], v[58:61]
	v_mfma_f32_16x16x32_f16 v[46:49], v[134:137], v[174:177], v[46:49]
	v_mfma_f32_16x16x32_f16 v[42:45], v[158:161], v[174:177], v[42:45]
	v_mfma_f32_16x16x32_f16 v[30:33], v[134:137], v[182:185], v[30:33]
	v_mfma_f32_16x16x32_f16 v[26:29], v[158:161], v[182:185], v[26:29]
	v_mfma_f32_16x16x32_f16 v[14:17], v[134:137], v[190:193], v[14:17]
	v_mfma_f32_16x16x32_f16 v[10:13], v[158:161], v[190:193], v[10:13]
	v_mfma_f32_16x16x32_f16 v[54:57], v[194:197], v[162:165], 0
	v_mfma_f32_16x16x32_f16 v[50:53], v[202:205], v[162:165], 0
	v_mfma_f32_16x16x32_f16 v[38:41], v[194:197], v[170:173], 0
	v_mfma_f32_16x16x32_f16 v[34:37], v[202:205], v[170:173], 0
	v_mfma_f32_16x16x32_f16 v[22:25], v[194:197], v[178:181], 0
	v_mfma_f32_16x16x32_f16 v[18:21], v[202:205], v[178:181], 0
	v_mfma_f32_16x16x32_f16 v[6:9], v[194:197], v[186:189], 0
	v_mfma_f32_16x16x32_f16 v[2:5], v[202:205], v[186:189], 0
	v_mfma_f32_16x16x32_f16 v[54:57], v[198:201], v[166:169], v[54:57]
	v_mfma_f32_16x16x32_f16 v[50:53], v[220:223], v[166:169], v[50:53]
	v_mfma_f32_16x16x32_f16 v[38:41], v[198:201], v[174:177], v[38:41]
	v_mfma_f32_16x16x32_f16 v[34:37], v[220:223], v[174:177], v[34:37]
	v_mfma_f32_16x16x32_f16 v[22:25], v[198:201], v[182:185], v[22:25]
	v_mfma_f32_16x16x32_f16 v[18:21], v[220:223], v[182:185], v[18:21]
	v_mfma_f32_16x16x32_f16 v[6:9], v[198:201], v[190:193], v[6:9]
	v_mfma_f32_16x16x32_f16 v[2:5], v[220:223], v[190:193], v[2:5]
	s_barrier
	s_add_i32 s45, 0, 0x18000
	v_add_u32_e32 v234, s45, v155
	ds_read_b128 v[130:133], v234
	ds_read_b128 v[134:137], v234 offset:1024
	ds_read_b128 v[148:151], v234 offset:2048
	ds_read_b128 v[158:161], v234 offset:3072
	s_add_u32 s48, s48, 0x80000
	s_addc_u32 s49, s49, 0
	s_mov_b32 m0, s73
	v_lshl_add_u64 v[232:233], s[48:49], 0, v[138:139]
	ds_read_b128 v[162:165], v157 offset:32768
	ds_read_b128 v[166:169], v157 offset:33792
	ds_read_b128 v[170:173], v157 offset:34816
	ds_read_b128 v[174:177], v157 offset:35840
	ds_read_b128 v[178:181], v157 offset:36864
	ds_read_b128 v[182:185], v157 offset:37888
	ds_read_b128 v[186:189], v157 offset:38912
	ds_read_b128 v[190:193], v157 offset:39936
	global_load_lds_dwordx4 v[232:233], off
	v_lshl_add_u64 v[232:233], s[48:49], 0, v[140:141]
	s_mov_b32 m0, s74
	s_nop 0
	global_load_lds_dwordx4 v[232:233], off
	s_waitcnt lgkmcnt(11)
	s_add_i32 s48, 0, 0x1c000
	s_add_i32 s45, s45, s72
	v_add_u32_e32 v214, s48, v155
	v_lshl_add_u64 v[152:153], v[152:153], 0, s[92:93]
	s_mov_b32 m0, s45
	ds_read_b128 v[194:197], v214
	ds_read_b128 v[198:201], v214 offset:1024
	ds_read_b128 v[202:205], v214 offset:2048
	ds_read_b128 v[220:223], v214 offset:3072
	s_waitcnt vmcnt(8) lgkmcnt(0)
	s_barrier
	v_mfma_f32_16x16x32_f16 v[126:129], v[130:133], v[162:165], v[126:129]
	v_mfma_f32_16x16x32_f16 v[122:125], v[148:151], v[162:165], v[122:125]
	v_mfma_f32_16x16x32_f16 v[110:113], v[130:133], v[170:173], v[110:113]
	v_mfma_f32_16x16x32_f16 v[106:109], v[148:151], v[170:173], v[106:109]
	v_mfma_f32_16x16x32_f16 v[94:97], v[130:133], v[178:181], v[94:97]
	v_mfma_f32_16x16x32_f16 v[90:93], v[148:151], v[178:181], v[90:93]
	v_mfma_f32_16x16x32_f16 v[78:81], v[130:133], v[186:189], v[78:81]
	v_mfma_f32_16x16x32_f16 v[74:77], v[148:151], v[186:189], v[74:77]
	v_mfma_f32_16x16x32_f16 v[126:129], v[134:137], v[166:169], v[126:129]
	v_mfma_f32_16x16x32_f16 v[122:125], v[158:161], v[166:169], v[122:125]
	v_mfma_f32_16x16x32_f16 v[110:113], v[134:137], v[174:177], v[110:113]
	v_mfma_f32_16x16x32_f16 v[106:109], v[158:161], v[174:177], v[106:109]
	v_mfma_f32_16x16x32_f16 v[94:97], v[134:137], v[182:185], v[94:97]
	v_mfma_f32_16x16x32_f16 v[90:93], v[158:161], v[182:185], v[90:93]
	v_mfma_f32_16x16x32_f16 v[78:81], v[134:137], v[190:193], v[78:81]
	v_mfma_f32_16x16x32_f16 v[74:77], v[158:161], v[190:193], v[74:77]
	v_mfma_f32_16x16x32_f16 v[118:121], v[194:197], v[162:165], v[118:121]
	v_mfma_f32_16x16x32_f16 v[114:117], v[202:205], v[162:165], v[114:117]
	v_mfma_f32_16x16x32_f16 v[102:105], v[194:197], v[170:173], v[102:105]
	v_mfma_f32_16x16x32_f16 v[98:101], v[202:205], v[170:173], v[98:101]
	v_mfma_f32_16x16x32_f16 v[86:89], v[194:197], v[178:181], v[86:89]
	v_mfma_f32_16x16x32_f16 v[82:85], v[202:205], v[178:181], v[82:85]
	v_mfma_f32_16x16x32_f16 v[70:73], v[194:197], v[186:189], v[70:73]
	v_mfma_f32_16x16x32_f16 v[66:69], v[202:205], v[186:189], v[66:69]
	v_mfma_f32_16x16x32_f16 v[118:121], v[198:201], v[166:169], v[118:121]
	v_mfma_f32_16x16x32_f16 v[114:117], v[220:223], v[166:169], v[114:117]
	v_mfma_f32_16x16x32_f16 v[102:105], v[198:201], v[174:177], v[102:105]
	v_mfma_f32_16x16x32_f16 v[98:101], v[220:223], v[174:177], v[98:101]
	v_mfma_f32_16x16x32_f16 v[86:89], v[198:201], v[182:185], v[86:89]
	v_mfma_f32_16x16x32_f16 v[82:85], v[220:223], v[182:185], v[82:85]
	v_mfma_f32_16x16x32_f16 v[70:73], v[198:201], v[190:193], v[70:73]
	v_mfma_f32_16x16x32_f16 v[66:69], v[220:223], v[190:193], v[66:69]
	s_barrier
; #define PG8_STAGE(bufoff, gbase, voff) do { _Pragma("unroll") for (int _i = 0; _i < 2; ++_i) \
;         __builtin_amdgcn_global_load_lds((const unsigned*)((const char*)(gbase) + (voff)[_i]), (LAS unsigned*)(lds + (bufoff) + ldsw + _i * 8192), 16, 0, 0); } while (0)
; #define PG8_LDA(dst, b, h) do { _Pragma("unroll") for (int m = 0; m < 4; ++m) _Pragma("unroll") for (int k = 0; k < 2; ++k) dst[m][k] = *(const LAS h16x8*)(lds + PG8_SA(b, h) + aoff + m * 2048 + k * 1024); } while (0)
; #define PG8_MMA(ai, bj, At, Bt_) do { __builtin_amdgcn_s_setprio(1); _Pragma("unroll") for (int m = 0; m < 4; ++m) _Pragma("unroll") for (int n = 0; n < 2; ++n) _Pragma("unroll") for (int k = 0; k < 2; ++k) \
;         acc[ai][bj][m][n] = __builtin_amdgcn_mfma_f32_16x16x32_f16(Bt_[n][k], At[m][k], acc[ai][bj][m][n], 0, 0, 0); __builtin_amdgcn_s_setprio(0); } while (0)
; #define PG8_WAIT_V(n) asm volatile("s_waitcnt vmcnt(" #n ")" ::: "memory")
; #define PG8_WAIT_L(n) asm volatile("s_waitcnt lgkmcnt(" #n ")" ::: "memory")
; #define PG8_BAR __builtin_amdgcn_s_barrier()
; #define PG8_SCHED __builtin_amdgcn_sched_barrier(0)
; template <class Epi, class AMap>
; __device__ __forceinline__ void gemm_phase(LAS unsigned char* lds, const AMap am, const int lda, const h16* Bt, const int ldb, const int M, const int N, const int K, const Epi& E) {
;     ...
;             PG8_LDA(At, 1, 1); PG8_STAGE(PG8_SA(1, 0), a3, voffA);
;             PG8_BAR; PG8_WAIT_L(0); PG8_MMA(1, 0, At, B0); PG8_BAR; PG8_SCHED;
;             PG8_STAGE(PG8_SB(1, 1), b3 + hstepB, voffB);
;             PG8_WAIT_V(6); PG8_BAR; PG8_MMA(1, 1, At, B1); PG8_BAR;
;         }
	global_load_lds_dwordx4 v[152:153], off
	v_lshl_add_u64 v[152:153], v[206:207], 0, s[92:93]
	s_add_i32 m0, s45, 0x2000
	s_nop 0
	global_load_lds_dwordx4 v[152:153], off
	s_mov_b32 m0, s75
	v_lshl_add_u64 v[152:153], v[212:213], 0, s[92:93]
	ds_read_b128 v[162:165], v157 offset:49152
	ds_read_b128 v[166:169], v157 offset:50176
	ds_read_b128 v[170:173], v157 offset:51200
	ds_read_b128 v[174:177], v157 offset:52224
	ds_read_b128 v[178:181], v157 offset:53248
	ds_read_b128 v[182:185], v157 offset:54272
	ds_read_b128 v[186:189], v157 offset:55296
	ds_read_b128 v[190:193], v157 offset:56320
	global_load_lds_dwordx4 v[152:153], off
	v_lshl_add_u64 v[152:153], v[224:225], 0, s[92:93]
	s_mov_b32 m0, s76
	s_nop 0
	global_load_lds_dwordx4 v[152:153], off
	s_add_u32 s40, s40, 0x80080
	s_addc_u32 s41, s41, 0
	s_add_i32 s45, s48, s72
	v_lshl_add_u64 v[232:233], s[40:41], 0, v[0:1]
	s_mov_b32 m0, s45
	s_nop 0
	global_load_lds_dwordx4 v[232:233], off
	v_lshl_add_u64 v[232:233], s[40:41], 0, v[142:143]
	s_add_i32 m0, s45, 0x2000
	s_nop 0
	global_load_lds_dwordx4 v[232:233], off
	s_add_i32 s43, s43, 2
	s_add_u32 s0, s0, 0x100
	s_addc_u32 s1, s1, 0
	s_add_u32 s21, s21, 0x100
	s_addc_u32 s35, s35, 0
	s_cmp_gt_u32 s43, 29
	s_waitcnt vmcnt(8) lgkmcnt(0)
	s_barrier
	v_mfma_f32_16x16x32_f16 v[62:65], v[130:133], v[162:165], v[62:65]
	v_mfma_f32_16x16x32_f16 v[58:61], v[148:151], v[162:165], v[58:61]
	v_mfma_f32_16x16x32_f16 v[46:49], v[130:133], v[170:173], v[46:49]
	v_mfma_f32_16x16x32_f16 v[42:45], v[148:151], v[170:173], v[42:45]
	v_mfma_f32_16x16x32_f16 v[30:33], v[130:133], v[178:181], v[30:33]
	v_mfma_f32_16x16x32_f16 v[26:29], v[148:151], v[178:181], v[26:29]
	v_mfma_f32_16x16x32_f16 v[14:17], v[130:133], v[186:189], v[14:17]
	v_mfma_f32_16x16x32_f16 v[10:13], v[148:151], v[186:189], v[10:13]
	v_mfma_f32_16x16x32_f16 v[62:65], v[134:137], v[166:169], v[62:65]
	v_mfma_f32_16x16x32_f16 v[58:61], v[158:161], v[166:169], v[58:61]
	v_mfma_f32_16x16x32_f16 v[46:49], v[134:137], v[174:177], v[46:49]
	v_mfma_f32_16x16x32_f16 v[42:45], v[158:161], v[174:177], v[42:45]
	v_mfma_f32_16x16x32_f16 v[30:33], v[134:137], v[182:185], v[30:33]
	v_mfma_f32_16x16x32_f16 v[26:29], v[158:161], v[182:185], v[26:29]
	v_mfma_f32_16x16x32_f16 v[14:17], v[134:137], v[190:193], v[14:17]
	v_mfma_f32_16x16x32_f16 v[10:13], v[158:161], v[190:193], v[10:13]
	v_mfma_f32_16x16x32_f16 v[54:57], v[194:197], v[162:165], v[54:57]
	v_mfma_f32_16x16x32_f16 v[50:53], v[202:205], v[162:165], v[50:53]
	v_mfma_f32_16x16x32_f16 v[38:41], v[194:197], v[170:173], v[38:41]
	v_mfma_f32_16x16x32_f16 v[34:37], v[202:205], v[170:173], v[34:37]
	v_mfma_f32_16x16x32_f16 v[22:25], v[194:197], v[178:181], v[22:25]
	v_mfma_f32_16x16x32_f16 v[18:21], v[202:205], v[178:181], v[18:21]
	v_mfma_f32_16x16x32_f16 v[6:9], v[194:197], v[186:189], v[6:9]
	v_mfma_f32_16x16x32_f16 v[2:5], v[202:205], v[186:189], v[2:5]
	v_mfma_f32_16x16x32_f16 v[54:57], v[198:201], v[166:169], v[54:57]
	v_mfma_f32_16x16x32_f16 v[50:53], v[220:223], v[166:169], v[50:53]
	v_mfma_f32_16x16x32_f16 v[38:41], v[198:201], v[174:177], v[38:41]
	v_mfma_f32_16x16x32_f16 v[34:37], v[220:223], v[174:177], v[34:37]
	v_mfma_f32_16x16x32_f16 v[22:25], v[198:201], v[182:185], v[22:25]
	v_mfma_f32_16x16x32_f16 v[18:21], v[220:223], v[182:185], v[18:21]
	v_mfma_f32_16x16x32_f16 v[6:9], v[198:201], v[190:193], v[6:9]
	v_mfma_f32_16x16x32_f16 v[2:5], v[220:223], v[190:193], v[2:5]
	s_barrier
	s_cbranch_scc1 .Lg4x_799
